# v026-full-4444-dma-smoothing-end-placement
# baseline (speedup 1.0000x reference)
; #define PG8_STAGE(bufoff, gbase, voff) do { _Pragma("unroll") for (int _i = 0; _i < 2; ++_i) \
;         __builtin_amdgcn_global_load_lds((const unsigned*)((const char*)(gbase) + (voff)[_i]), (PG8_LAS unsigned*)(lds + (bufoff) + ldsw + _i * 8192), 16, 0, 0); } while (0)
; #define PG8_LDA(dst, b, h) do { _Pragma("unroll") for (int m = 0; m < 4; ++m) _Pragma("unroll") for (int k = 0; k < 2; ++k) dst[m][k] = *(const PG8_LAS bf16x8*)(lds + PG8_SA(b, h) + aoff + m * 2048 + k * 1024); } while (0)
; #define PG8_LDB(dst, b, h) do { _Pragma("unroll") for (int n = 0; n < 2; ++n) _Pragma("unroll") for (int k = 0; k < 2; ++k) dst[n][k] = *(const PG8_LAS bf16x8*)(lds + PG8_SB(b, h) + boff + n * 2048 + k * 1024); } while (0)
; #define PG8_WAIT_V(n) asm volatile("s_waitcnt vmcnt(" #n ")" ::: "memory")
; #define PG8_WAIT_L(n) asm volatile("s_waitcnt lgkmcnt(" #n ")" ::: "memory")
; #define PG8_BAR __builtin_amdgcn_s_barrier()
; template <class Epi, class Sched, bool ALIGN_EPI = false, bool SP2 = false>
; __device__ __forceinline__ void gemm_phase(PG8_LAS unsigned char* lds, const Gemm g, const Sched& S, const Epi& E) {
;     ...
;         const bool has_next = S.next(ui + 1, nxt);
;         const char* nA = has_next ? (const char*)g.A + (size_t)nxt.pm * tstep + (size_t)nxt.k0 * kstepA : cA; const char* nB = has_next ? (const char*)g.Bt + (size_t)nxt.pn * tstep + (size_t)nxt.k0 * kstepB : cB;
;         for (int t = 0; t < nt; t += 2) {
;             const bool last = (t == nt - 2);
;             const char* a1 = cA + (size_t)(t + 1) * kstepA;
;             const char* a2 = last ? nA : cA + (size_t)(t + 2) * kstepA; const char* b2 = last ? nB : cB + (size_t)(t + 2) * kstepB;
;             const char* a3 = a2 + kstepA; const char* b3 = b2 + kstepB;
;             if (last && has_next) S.a_ready(nxt);
;             if constexpr (SP2) {
;             PG8_LDB(B0, 0, 0); PG8_LDB(B1, 0, 1); PG8_SCHED; PG8_LDA(At, 0, 0); PG8_STAGE(PG8_SA(1, 1), a1 + hstepA, voffA);
;             PG8_WAIT_V(8); PG8_WAIT_L(0); PG8_BAR; PG8_MMA(0, 0, At, B0); PG8_MMA(0, 1, At, B1); PG8_BAR; PG8_SCHED;
;             PG8_LDA(At, 0, 1); PG8_STAGE(PG8_SB(0, 0), b2, voffB); PG8_STAGE(PG8_SB(0, 1), b2 + hstepB, voffB); PG8_STAGE(PG8_SA(0, 0), a2, voffA);
;             PG8_WAIT_V(8); PG8_WAIT_L(0); PG8_BAR; PG8_MMA(1, 0, At, B0); PG8_MMA(1, 1, At, B1); PG8_BAR; PG8_SCHED;
.LBB0_277:
	s_sub_u32 s100, s40, 0x80000
	s_subb_u32 s101, s41, 0
	ds_read_b128 v[136:139], v129
	ds_read_b128 v[146:149], v129 offset:1024
	ds_read_b128 v[150:153], v129 offset:2048
	ds_read_b128 v[154:157], v129 offset:3072
	ds_read_b128 v[158:161], v143
	ds_read_b128 v[162:165], v143 offset:1024
	ds_read_b128 v[166:169], v143 offset:2048
	ds_read_b128 v[170:173], v143 offset:3072
	s_add_u32 s42, s40, 0xfff80080
	s_addc_u32 s43, s41, -1
	s_cmp_eq_u32 s56, 28
	s_cselect_b32 s45, s29, s43
	s_cselect_b32 s44, s52, s42
	s_cselect_b32 s43, s27, s55
	s_cselect_b32 s42, s53, s54
	ds_read_b128 v[174:177], v144
	ds_read_b128 v[178:181], v144 offset:1024
	ds_read_b128 v[182:185], v144 offset:2048
	ds_read_b128 v[204:207], v144 offset:3072
	ds_read_b128 v[208:211], v144 offset:4096
	ds_read_b128 v[212:215], v144 offset:5120
	ds_read_b128 v[216:219], v144 offset:6144
	ds_read_b128 v[220:223], v144 offset:7168
	s_mov_b32 m0, s15
	s_nop 0
	global_load_lds_dwordx4 v132, s[100:101]
	s_mov_b32 m0, s47
	s_nop 0
	global_load_lds_dwordx4 v134, s[100:101]
	s_add_i32 m0, s10, 0xc000
	s_nop 0
	global_load_lds_dwordx4 v132, s[40:41]
	s_add_i32 m0, s10, 0xe000
	s_nop 0
	global_load_lds_dwordx4 v134, s[40:41]
	s_waitcnt vmcnt(8)
	s_waitcnt lgkmcnt(0)
	s_setprio 1
	s_barrier
	v_mfma_f32_16x16x32_bf16 v[124:127], v[136:139], v[174:177], v[124:127]
	v_mfma_f32_16x16x32_bf16 v[120:123], v[150:153], v[174:177], v[120:123]
	v_mfma_f32_16x16x32_bf16 v[108:111], v[136:139], v[182:185], v[108:111]
	v_mfma_f32_16x16x32_bf16 v[104:107], v[150:153], v[182:185], v[104:107]
	v_mfma_f32_16x16x32_bf16 v[92:95], v[136:139], v[208:211], v[92:95]
	v_mfma_f32_16x16x32_bf16 v[88:91], v[150:153], v[208:211], v[88:91]
	v_mfma_f32_16x16x32_bf16 v[76:79], v[136:139], v[216:219], v[76:79]
	v_mfma_f32_16x16x32_bf16 v[72:75], v[150:153], v[216:219], v[72:75]
	v_mfma_f32_16x16x32_bf16 v[124:127], v[146:149], v[178:181], v[124:127]
	v_mfma_f32_16x16x32_bf16 v[120:123], v[154:157], v[178:181], v[120:123]
	v_mfma_f32_16x16x32_bf16 v[108:111], v[146:149], v[204:207], v[108:111]
	v_mfma_f32_16x16x32_bf16 v[104:107], v[154:157], v[204:207], v[104:107]
	v_mfma_f32_16x16x32_bf16 v[92:95], v[146:149], v[212:215], v[92:95]
	v_mfma_f32_16x16x32_bf16 v[88:91], v[154:157], v[212:215], v[88:91]
	v_mfma_f32_16x16x32_bf16 v[76:79], v[146:149], v[220:223], v[76:79]
	v_mfma_f32_16x16x32_bf16 v[72:75], v[154:157], v[220:223], v[72:75]
	v_mfma_f32_16x16x32_bf16 v[116:119], v[158:161], v[174:177], v[116:119]
	v_mfma_f32_16x16x32_bf16 v[112:115], v[166:169], v[174:177], v[112:115]
	v_mfma_f32_16x16x32_bf16 v[100:103], v[158:161], v[182:185], v[100:103]
	v_mfma_f32_16x16x32_bf16 v[96:99], v[166:169], v[182:185], v[96:99]
	v_mfma_f32_16x16x32_bf16 v[84:87], v[158:161], v[208:211], v[84:87]
	v_mfma_f32_16x16x32_bf16 v[80:83], v[166:169], v[208:211], v[80:83]
	v_mfma_f32_16x16x32_bf16 v[68:71], v[158:161], v[216:219], v[68:71]
	v_mfma_f32_16x16x32_bf16 v[64:67], v[166:169], v[216:219], v[64:67]
	v_mfma_f32_16x16x32_bf16 v[116:119], v[162:165], v[178:181], v[116:119]
	v_mfma_f32_16x16x32_bf16 v[112:115], v[170:173], v[178:181], v[112:115]
	v_mfma_f32_16x16x32_bf16 v[100:103], v[162:165], v[204:207], v[100:103]
	v_mfma_f32_16x16x32_bf16 v[96:99], v[170:173], v[204:207], v[96:99]
	v_mfma_f32_16x16x32_bf16 v[84:87], v[162:165], v[212:215], v[84:87]
	v_mfma_f32_16x16x32_bf16 v[80:83], v[170:173], v[212:215], v[80:83]
	v_mfma_f32_16x16x32_bf16 v[68:71], v[162:165], v[220:223], v[68:71]
	v_mfma_f32_16x16x32_bf16 v[64:67], v[170:173], v[220:223], v[64:67]
	s_barrier
	s_add_u32 s98, s44, s20
	s_addc_u32 s99, s45, s21
	s_setprio 0
	s_add_i32 s57, s49, s2
	s_mov_b32 m0, s57
	ds_read_b128 v[174:177], v144 offset:16384
	ds_read_b128 v[178:181], v144 offset:17408
	ds_read_b128 v[182:185], v144 offset:18432
	ds_read_b128 v[204:207], v144 offset:19456
	ds_read_b128 v[208:211], v144 offset:20480
	ds_read_b128 v[212:215], v144 offset:21504
	ds_read_b128 v[216:219], v144 offset:22528
	ds_read_b128 v[220:223], v144 offset:23552
	global_load_lds_dwordx4 v194, s[42:43]
	s_add_i32 m0, s57, 0x2000
	s_add_u32 s58, s42, 0x4000
	s_addc_u32 s59, s43, 0
	s_add_i32 s57, s50, s2
	global_load_lds_dwordx4 v198, s[42:43]
	s_mov_b32 m0, s57
	s_nop 0
	global_load_lds_dwordx4 v194, s[58:59]
	s_add_i32 m0, s57, 0x2000
	s_nop 0
	global_load_lds_dwordx4 v198, s[58:59]
	s_waitcnt vmcnt(6)
	s_waitcnt lgkmcnt(0)
	s_setprio 1
	s_barrier
	v_mfma_f32_16x16x32_bf16 v[60:63], v[136:139], v[174:177], v[60:63]
	v_mfma_f32_16x16x32_bf16 v[56:59], v[150:153], v[174:177], v[56:59]
	v_mfma_f32_16x16x32_bf16 v[44:47], v[136:139], v[182:185], v[44:47]
	v_mfma_f32_16x16x32_bf16 v[40:43], v[150:153], v[182:185], v[40:43]
	v_mfma_f32_16x16x32_bf16 v[28:31], v[136:139], v[208:211], v[28:31]
	v_mfma_f32_16x16x32_bf16 v[24:27], v[150:153], v[208:211], v[24:27]
	v_mfma_f32_16x16x32_bf16 v[12:15], v[136:139], v[216:219], v[12:15]
	v_mfma_f32_16x16x32_bf16 v[8:11], v[150:153], v[216:219], v[8:11]
	v_mfma_f32_16x16x32_bf16 v[60:63], v[146:149], v[178:181], v[60:63]
	v_mfma_f32_16x16x32_bf16 v[56:59], v[154:157], v[178:181], v[56:59]
	v_mfma_f32_16x16x32_bf16 v[44:47], v[146:149], v[204:207], v[44:47]
	v_mfma_f32_16x16x32_bf16 v[40:43], v[154:157], v[204:207], v[40:43]
	v_mfma_f32_16x16x32_bf16 v[28:31], v[146:149], v[212:215], v[28:31]
	v_mfma_f32_16x16x32_bf16 v[24:27], v[154:157], v[212:215], v[24:27]
	v_mfma_f32_16x16x32_bf16 v[12:15], v[146:149], v[220:223], v[12:15]
	v_mfma_f32_16x16x32_bf16 v[8:11], v[154:157], v[220:223], v[8:11]
	v_mfma_f32_16x16x32_bf16 v[52:55], v[158:161], v[174:177], v[52:55]
	v_mfma_f32_16x16x32_bf16 v[48:51], v[166:169], v[174:177], v[48:51]
	v_mfma_f32_16x16x32_bf16 v[36:39], v[158:161], v[182:185], v[36:39]
	v_mfma_f32_16x16x32_bf16 v[32:35], v[166:169], v[182:185], v[32:35]
	v_mfma_f32_16x16x32_bf16 v[20:23], v[158:161], v[208:211], v[20:23]
	v_mfma_f32_16x16x32_bf16 v[16:19], v[166:169], v[208:211], v[16:19]
	v_mfma_f32_16x16x32_bf16 v[4:7], v[158:161], v[216:219], v[4:7]
	v_mfma_f32_16x16x32_bf16 v[0:3], v[166:169], v[216:219], v[0:3]
	v_mfma_f32_16x16x32_bf16 v[52:55], v[162:165], v[178:181], v[52:55]
	v_mfma_f32_16x16x32_bf16 v[48:51], v[170:173], v[178:181], v[48:51]
	v_mfma_f32_16x16x32_bf16 v[36:39], v[162:165], v[204:207], v[36:39]
	v_mfma_f32_16x16x32_bf16 v[32:35], v[170:173], v[204:207], v[32:35]
	v_mfma_f32_16x16x32_bf16 v[20:23], v[162:165], v[212:215], v[20:23]
	v_mfma_f32_16x16x32_bf16 v[16:19], v[170:173], v[212:215], v[16:19]
	v_mfma_f32_16x16x32_bf16 v[4:7], v[162:165], v[220:223], v[4:7]
	v_mfma_f32_16x16x32_bf16 v[0:3], v[170:173], v[220:223], v[0:3]
	s_barrier
; #define PG8_STAGE(bufoff, gbase, voff) do { _Pragma("unroll") for (int _i = 0; _i < 2; ++_i) \
;         __builtin_amdgcn_global_load_lds((const unsigned*)((const char*)(gbase) + (voff)[_i]), (PG8_LAS unsigned*)(lds + (bufoff) + ldsw + _i * 8192), 16, 0, 0); } while (0)
; #define PG8_LDA(dst, b, h) do { _Pragma("unroll") for (int m = 0; m < 4; ++m) _Pragma("unroll") for (int k = 0; k < 2; ++k) dst[m][k] = *(const PG8_LAS bf16x8*)(lds + PG8_SA(b, h) + aoff + m * 2048 + k * 1024); } while (0)
; #define PG8_LDB(dst, b, h) do { _Pragma("unroll") for (int n = 0; n < 2; ++n) _Pragma("unroll") for (int k = 0; k < 2; ++k) dst[n][k] = *(const PG8_LAS bf16x8*)(lds + PG8_SB(b, h) + boff + n * 2048 + k * 1024); } while (0)
; #define PG8_MMA(ai, bj, At, Bt) do { __builtin_amdgcn_s_setprio(1); _Pragma("unroll") for (int m = 0; m < 4; ++m) _Pragma("unroll") for (int n = 0; n < 2; ++n) _Pragma("unroll") for (int k = 0; k < 2; ++k) \
;         acc[ai][bj][m][n] = __builtin_amdgcn_mfma_f32_16x16x32_bf16(Bt[n][k], At[m][k], acc[ai][bj][m][n], 0, 0, 0); __builtin_amdgcn_s_setprio(0); } while (0)
; #define PG8_WAIT_V(n) asm volatile("s_waitcnt vmcnt(" #n ")" ::: "memory")
; #define PG8_WAIT_L(n) asm volatile("s_waitcnt lgkmcnt(" #n ")" ::: "memory")
; #define PG8_BAR __builtin_amdgcn_s_barrier()
; #define PG8_SCHED __builtin_amdgcn_sched_barrier(0)
; template <class Epi, class Sched, bool ALIGN_EPI = false, bool SP2 = false>
; __device__ __forceinline__ void gemm_phase(PG8_LAS unsigned char* lds, const Gemm g, const Sched& S, const Epi& E) {
;     ...
;             PG8_LDB(B0, 1, 0); PG8_LDB(B1, 1, 1); PG8_SCHED; PG8_LDA(At, 1, 0); PG8_STAGE(PG8_SA(0, 1), a2 + hstepA, voffA);
;             PG8_WAIT_V(8); PG8_WAIT_L(0); PG8_BAR; PG8_MMA(0, 0, At, B0); PG8_MMA(0, 1, At, B1); PG8_BAR; PG8_SCHED;
;             PG8_LDA(At, 1, 1); PG8_STAGE(PG8_SB(1, 0), b3, voffB); PG8_STAGE(PG8_SB(1, 1), b3 + hstepB, voffB); PG8_STAGE(PG8_SA(1, 0), a3, voffA);
;             PG8_WAIT_V(8); PG8_WAIT_L(0); PG8_BAR; PG8_MMA(1, 0, At, B0); PG8_MMA(1, 1, At, B1); PG8_BAR; PG8_SCHED;
	s_setprio 0
	s_add_i32 s57, 0, 0x18000
	s_add_i32 s58, 0, 0x1c000
	v_add_u32_e32 v154, s57, v142
	v_add_u32_e32 v170, s58, v142
	ds_read_b128 v[136:139], v154
	ds_read_b128 v[146:149], v154 offset:1024
	ds_read_b128 v[150:153], v154 offset:2048
	ds_read_b128 v[154:157], v154 offset:3072
	ds_read_b128 v[158:161], v170
	ds_read_b128 v[162:165], v170 offset:1024
	ds_read_b128 v[166:169], v170 offset:2048
	ds_read_b128 v[170:173], v170 offset:3072
	s_mov_b32 m0, s10
	s_nop 0
	global_load_lds_dwordx4 v192, s[44:45]
	s_mov_b32 m0, s12
	s_nop 0
	global_load_lds_dwordx4 v196, s[44:45]
	s_add_u32 s44, s44, 0x80000
	s_addc_u32 s45, s45, 0
	s_mov_b32 m0, s13
	ds_read_b128 v[174:177], v144 offset:32768
	ds_read_b128 v[178:181], v144 offset:33792
	ds_read_b128 v[182:185], v144 offset:34816
	ds_read_b128 v[204:207], v144 offset:35840
	ds_read_b128 v[208:211], v144 offset:36864
	ds_read_b128 v[212:215], v144 offset:37888
	ds_read_b128 v[216:219], v144 offset:38912
	ds_read_b128 v[220:223], v144 offset:39936
	global_load_lds_dwordx4 v192, s[44:45]
	s_mov_b32 m0, s14
	s_nop 0
	global_load_lds_dwordx4 v196, s[44:45]
	s_waitcnt vmcnt(8)
	s_waitcnt lgkmcnt(0)
	s_setprio 1
	s_barrier
	v_mfma_f32_16x16x32_bf16 v[124:127], v[136:139], v[174:177], v[124:127]
	v_mfma_f32_16x16x32_bf16 v[120:123], v[150:153], v[174:177], v[120:123]
	v_mfma_f32_16x16x32_bf16 v[108:111], v[136:139], v[182:185], v[108:111]
	v_mfma_f32_16x16x32_bf16 v[104:107], v[150:153], v[182:185], v[104:107]
	v_mfma_f32_16x16x32_bf16 v[92:95], v[136:139], v[208:211], v[92:95]
	v_mfma_f32_16x16x32_bf16 v[88:91], v[150:153], v[208:211], v[88:91]
	v_mfma_f32_16x16x32_bf16 v[76:79], v[136:139], v[216:219], v[76:79]
	v_mfma_f32_16x16x32_bf16 v[72:75], v[150:153], v[216:219], v[72:75]
	v_mfma_f32_16x16x32_bf16 v[124:127], v[146:149], v[178:181], v[124:127]
	v_mfma_f32_16x16x32_bf16 v[120:123], v[154:157], v[178:181], v[120:123]
	v_mfma_f32_16x16x32_bf16 v[108:111], v[146:149], v[204:207], v[108:111]
	v_mfma_f32_16x16x32_bf16 v[104:107], v[154:157], v[204:207], v[104:107]
	v_mfma_f32_16x16x32_bf16 v[92:95], v[146:149], v[212:215], v[92:95]
	v_mfma_f32_16x16x32_bf16 v[88:91], v[154:157], v[212:215], v[88:91]
	v_mfma_f32_16x16x32_bf16 v[76:79], v[146:149], v[220:223], v[76:79]
	v_mfma_f32_16x16x32_bf16 v[72:75], v[154:157], v[220:223], v[72:75]
	v_mfma_f32_16x16x32_bf16 v[116:119], v[158:161], v[174:177], v[116:119]
	v_mfma_f32_16x16x32_bf16 v[112:115], v[166:169], v[174:177], v[112:115]
	v_mfma_f32_16x16x32_bf16 v[100:103], v[158:161], v[182:185], v[100:103]
	v_mfma_f32_16x16x32_bf16 v[96:99], v[166:169], v[182:185], v[96:99]
	v_mfma_f32_16x16x32_bf16 v[84:87], v[158:161], v[208:211], v[84:87]
	v_mfma_f32_16x16x32_bf16 v[80:83], v[166:169], v[208:211], v[80:83]
	v_mfma_f32_16x16x32_bf16 v[68:71], v[158:161], v[216:219], v[68:71]
	v_mfma_f32_16x16x32_bf16 v[64:67], v[166:169], v[216:219], v[64:67]
	v_mfma_f32_16x16x32_bf16 v[116:119], v[162:165], v[178:181], v[116:119]
	v_mfma_f32_16x16x32_bf16 v[112:115], v[170:173], v[178:181], v[112:115]
	v_mfma_f32_16x16x32_bf16 v[100:103], v[162:165], v[204:207], v[100:103]
	v_mfma_f32_16x16x32_bf16 v[96:99], v[170:173], v[204:207], v[96:99]
	v_mfma_f32_16x16x32_bf16 v[84:87], v[162:165], v[212:215], v[84:87]
	v_mfma_f32_16x16x32_bf16 v[80:83], v[170:173], v[212:215], v[80:83]
	v_mfma_f32_16x16x32_bf16 v[68:71], v[162:165], v[220:223], v[68:71]
	v_mfma_f32_16x16x32_bf16 v[64:67], v[170:173], v[220:223], v[64:67]
	s_barrier
	s_setprio 0
	s_add_u32 s44, s42, 0x8000
	s_addc_u32 s45, s43, 0
	s_add_i32 s57, s57, s2
	s_mov_b32 m0, s57
	ds_read_b128 v[174:177], v144 offset:49152
	ds_read_b128 v[178:181], v144 offset:50176
	ds_read_b128 v[182:185], v144 offset:51200
	ds_read_b128 v[204:207], v144 offset:52224
	ds_read_b128 v[208:211], v144 offset:53248
	ds_read_b128 v[212:215], v144 offset:54272
	ds_read_b128 v[216:219], v144 offset:55296
	ds_read_b128 v[220:223], v144 offset:56320
	global_load_lds_dwordx4 v194, s[44:45]
	s_add_i32 m0, s57, 0x2000
	s_add_u32 s42, s42, 0xc000
	s_addc_u32 s43, s43, 0
	global_load_lds_dwordx4 v198, s[44:45]
	s_add_i32 s44, s58, s2
	s_mov_b32 m0, s44
	s_nop 0
	global_load_lds_dwordx4 v194, s[42:43]
	s_add_i32 m0, s44, 0x2000
	s_nop 0
	global_load_lds_dwordx4 v198, s[42:43]
	s_waitcnt vmcnt(6)
	s_waitcnt lgkmcnt(0)
	s_setprio 1
	s_barrier
	v_mfma_f32_16x16x32_bf16 v[60:63], v[136:139], v[174:177], v[60:63]
	v_mfma_f32_16x16x32_bf16 v[56:59], v[150:153], v[174:177], v[56:59]
	v_mfma_f32_16x16x32_bf16 v[44:47], v[136:139], v[182:185], v[44:47]
	v_mfma_f32_16x16x32_bf16 v[40:43], v[150:153], v[182:185], v[40:43]
	v_mfma_f32_16x16x32_bf16 v[28:31], v[136:139], v[208:211], v[28:31]
	v_mfma_f32_16x16x32_bf16 v[24:27], v[150:153], v[208:211], v[24:27]
	v_mfma_f32_16x16x32_bf16 v[12:15], v[136:139], v[216:219], v[12:15]
	v_mfma_f32_16x16x32_bf16 v[8:11], v[150:153], v[216:219], v[8:11]
	v_mfma_f32_16x16x32_bf16 v[60:63], v[146:149], v[178:181], v[60:63]
	v_mfma_f32_16x16x32_bf16 v[56:59], v[154:157], v[178:181], v[56:59]
	v_mfma_f32_16x16x32_bf16 v[44:47], v[146:149], v[204:207], v[44:47]
	v_mfma_f32_16x16x32_bf16 v[40:43], v[154:157], v[204:207], v[40:43]
	v_mfma_f32_16x16x32_bf16 v[28:31], v[146:149], v[212:215], v[28:31]
	v_mfma_f32_16x16x32_bf16 v[24:27], v[154:157], v[212:215], v[24:27]
	v_mfma_f32_16x16x32_bf16 v[12:15], v[146:149], v[220:223], v[12:15]
	v_mfma_f32_16x16x32_bf16 v[8:11], v[154:157], v[220:223], v[8:11]
	v_mfma_f32_16x16x32_bf16 v[52:55], v[158:161], v[174:177], v[52:55]
	v_mfma_f32_16x16x32_bf16 v[48:51], v[166:169], v[174:177], v[48:51]
	v_mfma_f32_16x16x32_bf16 v[36:39], v[158:161], v[182:185], v[36:39]
	v_mfma_f32_16x16x32_bf16 v[32:35], v[166:169], v[182:185], v[32:35]
	v_mfma_f32_16x16x32_bf16 v[20:23], v[158:161], v[208:211], v[20:23]
	v_mfma_f32_16x16x32_bf16 v[16:19], v[166:169], v[208:211], v[16:19]
	v_mfma_f32_16x16x32_bf16 v[4:7], v[158:161], v[216:219], v[4:7]
	v_mfma_f32_16x16x32_bf16 v[0:3], v[166:169], v[216:219], v[0:3]
	v_mfma_f32_16x16x32_bf16 v[52:55], v[162:165], v[178:181], v[52:55]
	v_mfma_f32_16x16x32_bf16 v[48:51], v[170:173], v[178:181], v[48:51]
	v_mfma_f32_16x16x32_bf16 v[36:39], v[162:165], v[204:207], v[36:39]
	v_mfma_f32_16x16x32_bf16 v[32:35], v[170:173], v[204:207], v[32:35]
	v_mfma_f32_16x16x32_bf16 v[20:23], v[162:165], v[212:215], v[20:23]
	v_mfma_f32_16x16x32_bf16 v[16:19], v[170:173], v[212:215], v[16:19]
	v_mfma_f32_16x16x32_bf16 v[4:7], v[162:165], v[220:223], v[4:7]
	v_mfma_f32_16x16x32_bf16 v[0:3], v[170:173], v[220:223], v[0:3]
	s_barrier
	s_setprio 0
	s_add_i32 s56, s56, 2
	s_add_u32 s54, s54, 0x10000
	s_addc_u32 s55, s55, 0
	s_add_u32 s40, s40, 0x100
	s_addc_u32 s41, s41, 0
	s_cmp_gt_u32 s56, 29
	s_cbranch_scc0 .LBB0_277
	s_and_b64 vcc, exec, s[24:25]
	s_cbranch_vccz .LBB0_280
	s_barrier

; #define PG8_STAGE(bufoff, gbase, voff) do { _Pragma("unroll") for (int _i = 0; _i < 2; ++_i) \
;         __builtin_amdgcn_global_load_lds((const unsigned*)((const char*)(gbase) + (voff)[_i]), (PG8_LAS unsigned*)(lds + (bufoff) + ldsw + _i * 8192), 16, 0, 0); } while (0)
; #define PG8_LDA(dst, b, h) do { _Pragma("unroll") for (int m = 0; m < 4; ++m) _Pragma("unroll") for (int k = 0; k < 2; ++k) dst[m][k] = *(const PG8_LAS bf16x8*)(lds + PG8_SA(b, h) + aoff + m * 2048 + k * 1024); } while (0)
; #define PG8_LDB(dst, b, h) do { _Pragma("unroll") for (int n = 0; n < 2; ++n) _Pragma("unroll") for (int k = 0; k < 2; ++k) dst[n][k] = *(const PG8_LAS bf16x8*)(lds + PG8_SB(b, h) + boff + n * 2048 + k * 1024); } while (0)
; #define PG8_WAIT_V(n) asm volatile("s_waitcnt vmcnt(" #n ")" ::: "memory")
; #define PG8_WAIT_L(n) asm volatile("s_waitcnt lgkmcnt(" #n ")" ::: "memory")
; #define PG8_BAR __builtin_amdgcn_s_barrier()
; template <class Epi, class Sched, bool ALIGN_EPI = false, bool SP2 = false>
; __device__ __forceinline__ void gemm_phase(PG8_LAS unsigned char* lds, const Gemm g, const Sched& S, const Epi& E) {
;     ...
;         const bool has_next = S.next(ui + 1, nxt);
;         const char* nA = has_next ? (const char*)g.A + (size_t)nxt.pm * tstep + (size_t)nxt.k0 * kstepA : cA; const char* nB = has_next ? (const char*)g.Bt + (size_t)nxt.pn * tstep + (size_t)nxt.k0 * kstepB : cB;
;         for (int t = 0; t < nt; t += 2) {
;             const bool last = (t == nt - 2);
;             const char* a1 = cA + (size_t)(t + 1) * kstepA;
;             const char* a2 = last ? nA : cA + (size_t)(t + 2) * kstepA; const char* b2 = last ? nB : cB + (size_t)(t + 2) * kstepB;
;             const char* a3 = a2 + kstepA; const char* b3 = b2 + kstepB;
;             if (last && has_next) S.a_ready(nxt);
;             if constexpr (SP2) {
;             PG8_LDB(B0, 0, 0); PG8_LDB(B1, 0, 1); PG8_SCHED; PG8_LDA(At, 0, 0); PG8_STAGE(PG8_SA(1, 1), a1 + hstepA, voffA);
;             PG8_WAIT_V(8); PG8_WAIT_L(0); PG8_BAR; PG8_MMA(0, 0, At, B0); PG8_MMA(0, 1, At, B1); PG8_BAR; PG8_SCHED;
;             PG8_LDA(At, 0, 1); PG8_STAGE(PG8_SB(0, 0), b2, voffB); PG8_STAGE(PG8_SB(0, 1), b2 + hstepB, voffB); PG8_STAGE(PG8_SA(0, 0), a2, voffA);
;             PG8_WAIT_V(8); PG8_WAIT_L(0); PG8_BAR; PG8_MMA(1, 0, At, B0); PG8_MMA(1, 1, At, B1); PG8_BAR; PG8_SCHED;
.LBB0_360:
	s_sub_u32 s100, s34, 0x4000
	s_subb_u32 s101, s35, 0
	ds_read_b128 v[140:143], v185
	ds_read_b128 v[144:147], v185 offset:1024
	ds_read_b128 v[148:151], v185 offset:2048
	ds_read_b128 v[152:155], v185 offset:3072
	ds_read_b128 v[156:159], v201
	ds_read_b128 v[160:163], v201 offset:1024
	ds_read_b128 v[164:167], v201 offset:2048
	ds_read_b128 v[168:171], v201 offset:3072
	s_add_i32 s57, s36, 2
	s_add_u32 s37, s34, 0x4000
	s_addc_u32 s38, s35, 0
	s_cmp_eq_u32 s27, s36
	s_cselect_b32 s40, s28, s37
	s_cselect_b32 s41, s29, s38
	s_cselect_b32 s38, s30, s55
	s_cselect_b32 s39, s31, s56
	s_add_u32 s36, s40, 0x8000
	s_addc_u32 s37, s41, 0
	ds_read_b128 v[172:175], v204
	ds_read_b128 v[176:179], v204 offset:1024
	ds_read_b128 v[206:209], v204 offset:2048
	ds_read_b128 v[210:213], v204 offset:3072
	ds_read_b128 v[214:217], v204 offset:4096
	ds_read_b128 v[218:221], v204 offset:5120
	ds_read_b128 v[222:225], v204 offset:6144
	ds_read_b128 v[226:229], v204 offset:7168
	s_mov_b32 m0, s15
	s_nop 0
	global_load_lds_dwordx4 v132, s[100:101]
	s_mov_b32 m0, s42
	s_nop 0
	global_load_lds_dwordx4 v134, s[100:101]
	s_add_i32 m0, s10, 0xc000
	s_nop 0
	global_load_lds_dwordx4 v132, s[34:35]
	s_add_i32 m0, s10, 0xe000
	s_nop 0
	global_load_lds_dwordx4 v134, s[34:35]
	s_waitcnt vmcnt(8)
	s_waitcnt lgkmcnt(0)
	s_setprio 1
	s_barrier
	v_mfma_f32_16x16x32_bf16 v[124:127], v[140:143], v[172:175], v[124:127]
	v_mfma_f32_16x16x32_bf16 v[120:123], v[148:151], v[172:175], v[120:123]
	v_mfma_f32_16x16x32_bf16 v[108:111], v[140:143], v[206:209], v[108:111]
	v_mfma_f32_16x16x32_bf16 v[104:107], v[148:151], v[206:209], v[104:107]
	v_mfma_f32_16x16x32_bf16 v[92:95], v[140:143], v[214:217], v[92:95]
	v_mfma_f32_16x16x32_bf16 v[88:91], v[148:151], v[214:217], v[88:91]
	v_mfma_f32_16x16x32_bf16 v[76:79], v[140:143], v[222:225], v[76:79]
	v_mfma_f32_16x16x32_bf16 v[72:75], v[148:151], v[222:225], v[72:75]
	v_mfma_f32_16x16x32_bf16 v[124:127], v[144:147], v[176:179], v[124:127]
	v_mfma_f32_16x16x32_bf16 v[120:123], v[152:155], v[176:179], v[120:123]
	v_mfma_f32_16x16x32_bf16 v[108:111], v[144:147], v[210:213], v[108:111]
	v_mfma_f32_16x16x32_bf16 v[104:107], v[152:155], v[210:213], v[104:107]
	v_mfma_f32_16x16x32_bf16 v[92:95], v[144:147], v[218:221], v[92:95]
	v_mfma_f32_16x16x32_bf16 v[88:91], v[152:155], v[218:221], v[88:91]
	v_mfma_f32_16x16x32_bf16 v[76:79], v[144:147], v[226:229], v[76:79]
	v_mfma_f32_16x16x32_bf16 v[72:75], v[152:155], v[226:229], v[72:75]
	v_mfma_f32_16x16x32_bf16 v[116:119], v[156:159], v[172:175], v[116:119]
	v_mfma_f32_16x16x32_bf16 v[112:115], v[164:167], v[172:175], v[112:115]
	v_mfma_f32_16x16x32_bf16 v[100:103], v[156:159], v[206:209], v[100:103]
	v_mfma_f32_16x16x32_bf16 v[96:99], v[164:167], v[206:209], v[96:99]
	v_mfma_f32_16x16x32_bf16 v[84:87], v[156:159], v[214:217], v[84:87]
	v_mfma_f32_16x16x32_bf16 v[80:83], v[164:167], v[214:217], v[80:83]
	v_mfma_f32_16x16x32_bf16 v[68:71], v[156:159], v[222:225], v[68:71]
	v_mfma_f32_16x16x32_bf16 v[64:67], v[164:167], v[222:225], v[64:67]
	v_mfma_f32_16x16x32_bf16 v[116:119], v[160:163], v[176:179], v[116:119]
	v_mfma_f32_16x16x32_bf16 v[112:115], v[168:171], v[176:179], v[112:115]
	v_mfma_f32_16x16x32_bf16 v[100:103], v[160:163], v[210:213], v[100:103]
	v_mfma_f32_16x16x32_bf16 v[96:99], v[168:171], v[210:213], v[96:99]
	v_mfma_f32_16x16x32_bf16 v[84:87], v[160:163], v[218:221], v[84:87]
	v_mfma_f32_16x16x32_bf16 v[80:83], v[168:171], v[218:221], v[80:83]
	v_mfma_f32_16x16x32_bf16 v[68:71], v[160:163], v[226:229], v[68:71]
	v_mfma_f32_16x16x32_bf16 v[64:67], v[168:171], v[226:229], v[64:67]
	s_barrier
	s_setprio 0
	s_add_i32 s58, s44, s2
	s_mov_b32 m0, s58
	ds_read_b128 v[172:175], v204 offset:16384
	ds_read_b128 v[176:179], v204 offset:17408
	ds_read_b128 v[206:209], v204 offset:18432
	ds_read_b128 v[210:213], v204 offset:19456
	ds_read_b128 v[214:217], v204 offset:20480
	ds_read_b128 v[218:221], v204 offset:21504
	ds_read_b128 v[222:225], v204 offset:22528
	ds_read_b128 v[226:229], v204 offset:23552
	global_load_lds_dwordx4 v128, s[38:39]
	s_add_i32 m0, s58, 0x2000
	s_add_u32 s58, s38, 0x4000
	s_addc_u32 s59, s39, 0
	s_add_i32 s60, s45, s2
	global_load_lds_dwordx4 v130, s[38:39]
	s_mov_b32 m0, s60
	s_nop 0
	global_load_lds_dwordx4 v128, s[58:59]
	s_add_i32 m0, s60, 0x2000
	s_nop 0
	global_load_lds_dwordx4 v130, s[58:59]
	s_waitcnt vmcnt(6)
	s_waitcnt lgkmcnt(0)
	s_setprio 1
	s_barrier
	v_mfma_f32_16x16x32_bf16 v[60:63], v[140:143], v[172:175], v[60:63]
	v_mfma_f32_16x16x32_bf16 v[56:59], v[148:151], v[172:175], v[56:59]
	v_mfma_f32_16x16x32_bf16 v[44:47], v[140:143], v[206:209], v[44:47]
	v_mfma_f32_16x16x32_bf16 v[40:43], v[148:151], v[206:209], v[40:43]
	v_mfma_f32_16x16x32_bf16 v[28:31], v[140:143], v[214:217], v[28:31]
	v_mfma_f32_16x16x32_bf16 v[24:27], v[148:151], v[214:217], v[24:27]
	v_mfma_f32_16x16x32_bf16 v[12:15], v[140:143], v[222:225], v[12:15]
	v_mfma_f32_16x16x32_bf16 v[8:11], v[148:151], v[222:225], v[8:11]
	v_mfma_f32_16x16x32_bf16 v[60:63], v[144:147], v[176:179], v[60:63]
	v_mfma_f32_16x16x32_bf16 v[56:59], v[152:155], v[176:179], v[56:59]
	v_mfma_f32_16x16x32_bf16 v[44:47], v[144:147], v[210:213], v[44:47]
	v_mfma_f32_16x16x32_bf16 v[40:43], v[152:155], v[210:213], v[40:43]
	v_mfma_f32_16x16x32_bf16 v[28:31], v[144:147], v[218:221], v[28:31]
	v_mfma_f32_16x16x32_bf16 v[24:27], v[152:155], v[218:221], v[24:27]
	v_mfma_f32_16x16x32_bf16 v[12:15], v[144:147], v[226:229], v[12:15]
	v_mfma_f32_16x16x32_bf16 v[8:11], v[152:155], v[226:229], v[8:11]
	v_mfma_f32_16x16x32_bf16 v[52:55], v[156:159], v[172:175], v[52:55]
	v_mfma_f32_16x16x32_bf16 v[48:51], v[164:167], v[172:175], v[48:51]
	v_mfma_f32_16x16x32_bf16 v[36:39], v[156:159], v[206:209], v[36:39]
	v_mfma_f32_16x16x32_bf16 v[32:35], v[164:167], v[206:209], v[32:35]
	v_mfma_f32_16x16x32_bf16 v[20:23], v[156:159], v[214:217], v[20:23]
	v_mfma_f32_16x16x32_bf16 v[16:19], v[164:167], v[214:217], v[16:19]
	v_mfma_f32_16x16x32_bf16 v[4:7], v[156:159], v[222:225], v[4:7]
	v_mfma_f32_16x16x32_bf16 v[0:3], v[164:167], v[222:225], v[0:3]
	v_mfma_f32_16x16x32_bf16 v[52:55], v[160:163], v[176:179], v[52:55]
	v_mfma_f32_16x16x32_bf16 v[48:51], v[168:171], v[176:179], v[48:51]
	v_mfma_f32_16x16x32_bf16 v[36:39], v[160:163], v[210:213], v[36:39]
	v_mfma_f32_16x16x32_bf16 v[32:35], v[168:171], v[210:213], v[32:35]
	v_mfma_f32_16x16x32_bf16 v[20:23], v[160:163], v[218:221], v[20:23]
	v_mfma_f32_16x16x32_bf16 v[16:19], v[168:171], v[218:221], v[16:19]
	v_mfma_f32_16x16x32_bf16 v[4:7], v[160:163], v[226:229], v[4:7]
	v_mfma_f32_16x16x32_bf16 v[0:3], v[168:171], v[226:229], v[0:3]
	s_barrier
; #define PG8_STAGE(bufoff, gbase, voff) do { _Pragma("unroll") for (int _i = 0; _i < 2; ++_i) \
;         __builtin_amdgcn_global_load_lds((const unsigned*)((const char*)(gbase) + (voff)[_i]), (PG8_LAS unsigned*)(lds + (bufoff) + ldsw + _i * 8192), 16, 0, 0); } while (0)
; #define PG8_LDA(dst, b, h) do { _Pragma("unroll") for (int m = 0; m < 4; ++m) _Pragma("unroll") for (int k = 0; k < 2; ++k) dst[m][k] = *(const PG8_LAS bf16x8*)(lds + PG8_SA(b, h) + aoff + m * 2048 + k * 1024); } while (0)
; #define PG8_LDB(dst, b, h) do { _Pragma("unroll") for (int n = 0; n < 2; ++n) _Pragma("unroll") for (int k = 0; k < 2; ++k) dst[n][k] = *(const PG8_LAS bf16x8*)(lds + PG8_SB(b, h) + boff + n * 2048 + k * 1024); } while (0)
; #define PG8_MMA(ai, bj, At, Bt) do { __builtin_amdgcn_s_setprio(1); _Pragma("unroll") for (int m = 0; m < 4; ++m) _Pragma("unroll") for (int n = 0; n < 2; ++n) _Pragma("unroll") for (int k = 0; k < 2; ++k) \
;         acc[ai][bj][m][n] = __builtin_amdgcn_mfma_f32_16x16x32_bf16(Bt[n][k], At[m][k], acc[ai][bj][m][n], 0, 0, 0); __builtin_amdgcn_s_setprio(0); } while (0)
; #define PG8_WAIT_V(n) asm volatile("s_waitcnt vmcnt(" #n ")" ::: "memory")
; #define PG8_WAIT_L(n) asm volatile("s_waitcnt lgkmcnt(" #n ")" ::: "memory")
; #define PG8_BAR __builtin_amdgcn_s_barrier()
; #define PG8_SCHED __builtin_amdgcn_sched_barrier(0)
; template <class Epi, class Sched, bool ALIGN_EPI = false, bool SP2 = false>
; __device__ __forceinline__ void gemm_phase(PG8_LAS unsigned char* lds, const Gemm g, const Sched& S, const Epi& E) {
;     ...
;             PG8_LDB(B0, 1, 0); PG8_LDB(B1, 1, 1); PG8_SCHED; PG8_LDA(At, 1, 0); PG8_STAGE(PG8_SA(0, 1), a2 + hstepA, voffA);
;             PG8_WAIT_V(8); PG8_WAIT_L(0); PG8_BAR; PG8_MMA(0, 0, At, B0); PG8_MMA(0, 1, At, B1); PG8_BAR; PG8_SCHED;
;             PG8_LDA(At, 1, 1); PG8_STAGE(PG8_SB(1, 0), b3, voffB); PG8_STAGE(PG8_SB(1, 1), b3 + hstepB, voffB); PG8_STAGE(PG8_SA(1, 0), a3, voffA);
;             PG8_WAIT_V(8); PG8_WAIT_L(0); PG8_BAR; PG8_MMA(1, 0, At, B0); PG8_MMA(1, 1, At, B1); PG8_BAR; PG8_SCHED;
	s_setprio 0
	s_add_i32 s58, 0, 0x18000
	s_add_i32 s59, 0, 0x1c000
	v_add_u32_e32 v152, s58, v183
	v_add_u32_e32 v168, s59, v183
	ds_read_b128 v[140:143], v152
	ds_read_b128 v[144:147], v152 offset:1024
	ds_read_b128 v[148:151], v152 offset:2048
	ds_read_b128 v[152:155], v152 offset:3072
	ds_read_b128 v[156:159], v168
	ds_read_b128 v[160:163], v168 offset:1024
	ds_read_b128 v[164:167], v168 offset:2048
	ds_read_b128 v[168:171], v168 offset:3072
	s_mov_b32 m0, s10
	s_nop 0
	global_load_lds_dwordx4 v128, s[40:41]
	s_mov_b32 m0, s12
	s_nop 0
	global_load_lds_dwordx4 v130, s[40:41]
	s_add_u32 s40, s40, 0x4000
	s_addc_u32 s41, s41, 0
	s_mov_b32 m0, s13
	ds_read_b128 v[172:175], v204 offset:32768
	ds_read_b128 v[176:179], v204 offset:33792
	ds_read_b128 v[206:209], v204 offset:34816
	ds_read_b128 v[210:213], v204 offset:35840
	ds_read_b128 v[214:217], v204 offset:36864
	ds_read_b128 v[218:221], v204 offset:37888
	ds_read_b128 v[222:225], v204 offset:38912
	ds_read_b128 v[226:229], v204 offset:39936
	global_load_lds_dwordx4 v128, s[40:41]
	s_mov_b32 m0, s14
	s_nop 0
	global_load_lds_dwordx4 v130, s[40:41]
	s_waitcnt vmcnt(8)
	s_waitcnt lgkmcnt(0)
	s_setprio 1
	s_barrier
	v_mfma_f32_16x16x32_bf16 v[124:127], v[140:143], v[172:175], v[124:127]
	v_mfma_f32_16x16x32_bf16 v[120:123], v[148:151], v[172:175], v[120:123]
	v_mfma_f32_16x16x32_bf16 v[108:111], v[140:143], v[206:209], v[108:111]
	v_mfma_f32_16x16x32_bf16 v[104:107], v[148:151], v[206:209], v[104:107]
	v_mfma_f32_16x16x32_bf16 v[92:95], v[140:143], v[214:217], v[92:95]
	v_mfma_f32_16x16x32_bf16 v[88:91], v[148:151], v[214:217], v[88:91]
	v_mfma_f32_16x16x32_bf16 v[76:79], v[140:143], v[222:225], v[76:79]
	v_mfma_f32_16x16x32_bf16 v[72:75], v[148:151], v[222:225], v[72:75]
	v_mfma_f32_16x16x32_bf16 v[124:127], v[144:147], v[176:179], v[124:127]
	v_mfma_f32_16x16x32_bf16 v[120:123], v[152:155], v[176:179], v[120:123]
	v_mfma_f32_16x16x32_bf16 v[108:111], v[144:147], v[210:213], v[108:111]
	v_mfma_f32_16x16x32_bf16 v[104:107], v[152:155], v[210:213], v[104:107]
	v_mfma_f32_16x16x32_bf16 v[92:95], v[144:147], v[218:221], v[92:95]
	v_mfma_f32_16x16x32_bf16 v[88:91], v[152:155], v[218:221], v[88:91]
	v_mfma_f32_16x16x32_bf16 v[76:79], v[144:147], v[226:229], v[76:79]
	v_mfma_f32_16x16x32_bf16 v[72:75], v[152:155], v[226:229], v[72:75]
	v_mfma_f32_16x16x32_bf16 v[116:119], v[156:159], v[172:175], v[116:119]
	v_mfma_f32_16x16x32_bf16 v[112:115], v[164:167], v[172:175], v[112:115]
	v_mfma_f32_16x16x32_bf16 v[100:103], v[156:159], v[206:209], v[100:103]
	v_mfma_f32_16x16x32_bf16 v[96:99], v[164:167], v[206:209], v[96:99]
	v_mfma_f32_16x16x32_bf16 v[84:87], v[156:159], v[214:217], v[84:87]
	v_mfma_f32_16x16x32_bf16 v[80:83], v[164:167], v[214:217], v[80:83]
	v_mfma_f32_16x16x32_bf16 v[68:71], v[156:159], v[222:225], v[68:71]
	v_mfma_f32_16x16x32_bf16 v[64:67], v[164:167], v[222:225], v[64:67]
	v_mfma_f32_16x16x32_bf16 v[116:119], v[160:163], v[176:179], v[116:119]
	v_mfma_f32_16x16x32_bf16 v[112:115], v[168:171], v[176:179], v[112:115]
	v_mfma_f32_16x16x32_bf16 v[100:103], v[160:163], v[210:213], v[100:103]
	v_mfma_f32_16x16x32_bf16 v[96:99], v[168:171], v[210:213], v[96:99]
	v_mfma_f32_16x16x32_bf16 v[84:87], v[160:163], v[218:221], v[84:87]
	v_mfma_f32_16x16x32_bf16 v[80:83], v[168:171], v[218:221], v[80:83]
	v_mfma_f32_16x16x32_bf16 v[68:71], v[160:163], v[226:229], v[68:71]
	v_mfma_f32_16x16x32_bf16 v[64:67], v[168:171], v[226:229], v[64:67]
	s_barrier
	s_setprio 0
	s_add_u32 s40, s38, 0x8000
	s_addc_u32 s41, s39, 0
	s_add_i32 s58, s58, s2
	s_mov_b32 m0, s58
	ds_read_b128 v[172:175], v204 offset:49152
	ds_read_b128 v[176:179], v204 offset:50176
	ds_read_b128 v[206:209], v204 offset:51200
	ds_read_b128 v[210:213], v204 offset:52224
	ds_read_b128 v[214:217], v204 offset:53248
	ds_read_b128 v[218:221], v204 offset:54272
	ds_read_b128 v[222:225], v204 offset:55296
	ds_read_b128 v[226:229], v204 offset:56320
	global_load_lds_dwordx4 v128, s[40:41]
	s_add_i32 m0, s58, 0x2000
	s_add_u32 s38, s38, 0xc000
	s_addc_u32 s39, s39, 0
	global_load_lds_dwordx4 v130, s[40:41]
	s_add_i32 s40, s59, s2
	s_mov_b32 m0, s40
	s_nop 0
	global_load_lds_dwordx4 v128, s[38:39]
	s_add_i32 m0, s40, 0x2000
	s_nop 0
	global_load_lds_dwordx4 v130, s[38:39]
	s_waitcnt vmcnt(6)
	s_waitcnt lgkmcnt(0)
	s_setprio 1
	s_barrier
	v_mfma_f32_16x16x32_bf16 v[60:63], v[140:143], v[172:175], v[60:63]
	v_mfma_f32_16x16x32_bf16 v[56:59], v[148:151], v[172:175], v[56:59]
	v_mfma_f32_16x16x32_bf16 v[44:47], v[140:143], v[206:209], v[44:47]
	v_mfma_f32_16x16x32_bf16 v[40:43], v[148:151], v[206:209], v[40:43]
	v_mfma_f32_16x16x32_bf16 v[28:31], v[140:143], v[214:217], v[28:31]
	v_mfma_f32_16x16x32_bf16 v[24:27], v[148:151], v[214:217], v[24:27]
	v_mfma_f32_16x16x32_bf16 v[12:15], v[140:143], v[222:225], v[12:15]
	v_mfma_f32_16x16x32_bf16 v[8:11], v[148:151], v[222:225], v[8:11]
	v_mfma_f32_16x16x32_bf16 v[60:63], v[144:147], v[176:179], v[60:63]
	v_mfma_f32_16x16x32_bf16 v[56:59], v[152:155], v[176:179], v[56:59]
	v_mfma_f32_16x16x32_bf16 v[44:47], v[144:147], v[210:213], v[44:47]
	v_mfma_f32_16x16x32_bf16 v[40:43], v[152:155], v[210:213], v[40:43]
	v_mfma_f32_16x16x32_bf16 v[28:31], v[144:147], v[218:221], v[28:31]
	v_mfma_f32_16x16x32_bf16 v[24:27], v[152:155], v[218:221], v[24:27]
	v_mfma_f32_16x16x32_bf16 v[12:15], v[144:147], v[226:229], v[12:15]
	v_mfma_f32_16x16x32_bf16 v[8:11], v[152:155], v[226:229], v[8:11]
	v_mfma_f32_16x16x32_bf16 v[52:55], v[156:159], v[172:175], v[52:55]
	v_mfma_f32_16x16x32_bf16 v[48:51], v[164:167], v[172:175], v[48:51]
	v_mfma_f32_16x16x32_bf16 v[36:39], v[156:159], v[206:209], v[36:39]
	v_mfma_f32_16x16x32_bf16 v[32:35], v[164:167], v[206:209], v[32:35]
	v_mfma_f32_16x16x32_bf16 v[20:23], v[156:159], v[214:217], v[20:23]
	v_mfma_f32_16x16x32_bf16 v[16:19], v[164:167], v[214:217], v[16:19]
	v_mfma_f32_16x16x32_bf16 v[4:7], v[156:159], v[222:225], v[4:7]
	v_mfma_f32_16x16x32_bf16 v[0:3], v[164:167], v[222:225], v[0:3]
	v_mfma_f32_16x16x32_bf16 v[52:55], v[160:163], v[176:179], v[52:55]
	v_mfma_f32_16x16x32_bf16 v[48:51], v[168:171], v[176:179], v[48:51]
	v_mfma_f32_16x16x32_bf16 v[36:39], v[160:163], v[210:213], v[36:39]
	v_mfma_f32_16x16x32_bf16 v[32:35], v[168:171], v[210:213], v[32:35]
	v_mfma_f32_16x16x32_bf16 v[20:23], v[160:163], v[218:221], v[20:23]
	v_mfma_f32_16x16x32_bf16 v[16:19], v[168:171], v[218:221], v[16:19]
	v_mfma_f32_16x16x32_bf16 v[4:7], v[160:163], v[226:229], v[4:7]
	v_mfma_f32_16x16x32_bf16 v[0:3], v[168:171], v[226:229], v[0:3]
	s_barrier
	s_setprio 0
	s_add_u32 s34, s34, 0x10000
	s_addc_u32 s35, s35, 0
	s_add_u32 s55, s55, 0x10000
	s_addc_u32 s56, s56, 0
	s_cmp_ge_i32 s57, s54
	s_mov_b32 s36, s57
	s_cbranch_scc0 .LBB0_360
	s_and_b64 vcc, exec, s[24:25]
	s_cbranch_vccnz .LBB0_365
	s_mov_b64 s[34:35], -1
	s_cmp_gt_i32 s20, -1
	v_lshl_or_b32 v140, s53, 8, v184
	s_cbranch_scc1 .LBB0_366

; #define PG8_STAGE(bufoff, gbase, voff) do { _Pragma("unroll") for (int _i = 0; _i < 2; ++_i) \
;         __builtin_amdgcn_global_load_lds((const unsigned*)((const char*)(gbase) + (voff)[_i]), (PG8_LAS unsigned*)(lds + (bufoff) + ldsw + _i * 8192), 16, 0, 0); } while (0)
; #define PG8_LDA(dst, b, h) do { _Pragma("unroll") for (int m = 0; m < 4; ++m) _Pragma("unroll") for (int k = 0; k < 2; ++k) dst[m][k] = *(const PG8_LAS bf16x8*)(lds + PG8_SA(b, h) + aoff + m * 2048 + k * 1024); } while (0)
; #define PG8_LDB(dst, b, h) do { _Pragma("unroll") for (int n = 0; n < 2; ++n) _Pragma("unroll") for (int k = 0; k < 2; ++k) dst[n][k] = *(const PG8_LAS bf16x8*)(lds + PG8_SB(b, h) + boff + n * 2048 + k * 1024); } while (0)
; #define PG8_WAIT_V(n) asm volatile("s_waitcnt vmcnt(" #n ")" ::: "memory")
; #define PG8_WAIT_L(n) asm volatile("s_waitcnt lgkmcnt(" #n ")" ::: "memory")
; #define PG8_BAR __builtin_amdgcn_s_barrier()
; template <class Epi, class Sched, bool ALIGN_EPI = false, bool SP2 = false>
; __device__ __forceinline__ void gemm_phase(PG8_LAS unsigned char* lds, const Gemm g, const Sched& S, const Epi& E) {
;     ...
;         const bool has_next = S.next(ui + 1, nxt);
;         const char* nA = has_next ? (const char*)g.A + (size_t)nxt.pm * tstep + (size_t)nxt.k0 * kstepA : cA; const char* nB = has_next ? (const char*)g.Bt + (size_t)nxt.pn * tstep + (size_t)nxt.k0 * kstepB : cB;
;         for (int t = 0; t < nt; t += 2) {
;             const bool last = (t == nt - 2);
;             const char* a1 = cA + (size_t)(t + 1) * kstepA;
;             const char* a2 = last ? nA : cA + (size_t)(t + 2) * kstepA; const char* b2 = last ? nB : cB + (size_t)(t + 2) * kstepB;
;             const char* a3 = a2 + kstepA; const char* b3 = b2 + kstepB;
;             if (last && has_next) S.a_ready(nxt);
;             if constexpr (SP2) {
;             PG8_LDB(B0, 0, 0); PG8_LDB(B1, 0, 1); PG8_SCHED; PG8_LDA(At, 0, 0); PG8_STAGE(PG8_SA(1, 1), a1 + hstepA, voffA);
;             PG8_WAIT_V(8); PG8_WAIT_L(0); PG8_BAR; PG8_MMA(0, 0, At, B0); PG8_MMA(0, 1, At, B1); PG8_BAR; PG8_SCHED;
;             PG8_LDA(At, 0, 1); PG8_STAGE(PG8_SB(0, 0), b2, voffB); PG8_STAGE(PG8_SB(0, 1), b2 + hstepB, voffB); PG8_STAGE(PG8_SA(0, 0), a2, voffA);
;             PG8_WAIT_V(8); PG8_WAIT_L(0); PG8_BAR; PG8_MMA(1, 0, At, B0); PG8_MMA(1, 1, At, B1); PG8_BAR; PG8_SCHED;
.LBB0_616:
	s_sub_u32 s100, s38, 0x80000
	s_subb_u32 s101, s39, 0
	ds_read_b128 v[132:135], v147
	ds_read_b128 v[136:139], v147 offset:1024
	ds_read_b128 v[140:143], v147 offset:2048
	ds_read_b128 v[152:155], v147 offset:3072
	ds_read_b128 v[156:159], v148
	ds_read_b128 v[160:163], v148 offset:1024
	ds_read_b128 v[164:167], v148 offset:2048
	ds_read_b128 v[168:171], v148 offset:3072
	s_add_u32 s40, s38, 0xfff80080
	s_addc_u32 s41, s39, -1
	s_cmp_eq_u32 s55, 28
	s_cselect_b32 s43, s1, s41
	s_cselect_b32 s42, s27, s40
	s_cselect_b32 s41, s25, s54
	s_cselect_b32 s40, s37, s53
	ds_read_b128 v[172:175], v149
	ds_read_b128 v[176:179], v149 offset:1024
	ds_read_b128 v[180:183], v149 offset:2048
	ds_read_b128 v[204:207], v149 offset:3072
	ds_read_b128 v[208:211], v149 offset:4096
	ds_read_b128 v[212:215], v149 offset:5120
	ds_read_b128 v[216:219], v149 offset:6144
	ds_read_b128 v[220:223], v149 offset:7168
	s_mov_b32 m0, s48
	s_nop 0
	global_load_lds_dwordx4 v128, s[100:101]
	s_mov_b32 m0, s49
	s_nop 0
	global_load_lds_dwordx4 v130, s[100:101]
	s_add_i32 m0, s13, 0xc000
	s_nop 0
	global_load_lds_dwordx4 v128, s[38:39]
	s_add_i32 m0, s13, 0xe000
	s_nop 0
	global_load_lds_dwordx4 v130, s[38:39]
	s_waitcnt vmcnt(8)
	s_waitcnt lgkmcnt(0)
	s_setprio 1
	s_barrier
	v_mfma_f32_16x16x32_bf16 v[124:127], v[132:135], v[172:175], v[124:127]
	v_mfma_f32_16x16x32_bf16 v[120:123], v[140:143], v[172:175], v[120:123]
	v_mfma_f32_16x16x32_bf16 v[108:111], v[132:135], v[180:183], v[108:111]
	v_mfma_f32_16x16x32_bf16 v[104:107], v[140:143], v[180:183], v[104:107]
	v_mfma_f32_16x16x32_bf16 v[92:95], v[132:135], v[208:211], v[92:95]
	v_mfma_f32_16x16x32_bf16 v[88:91], v[140:143], v[208:211], v[88:91]
	v_mfma_f32_16x16x32_bf16 v[76:79], v[132:135], v[216:219], v[76:79]
	v_mfma_f32_16x16x32_bf16 v[72:75], v[140:143], v[216:219], v[72:75]
	v_mfma_f32_16x16x32_bf16 v[124:127], v[136:139], v[176:179], v[124:127]
	v_mfma_f32_16x16x32_bf16 v[120:123], v[152:155], v[176:179], v[120:123]
	v_mfma_f32_16x16x32_bf16 v[108:111], v[136:139], v[204:207], v[108:111]
	v_mfma_f32_16x16x32_bf16 v[104:107], v[152:155], v[204:207], v[104:107]
	v_mfma_f32_16x16x32_bf16 v[92:95], v[136:139], v[212:215], v[92:95]
	v_mfma_f32_16x16x32_bf16 v[88:91], v[152:155], v[212:215], v[88:91]
	v_mfma_f32_16x16x32_bf16 v[76:79], v[136:139], v[220:223], v[76:79]
	v_mfma_f32_16x16x32_bf16 v[72:75], v[152:155], v[220:223], v[72:75]
	v_mfma_f32_16x16x32_bf16 v[116:119], v[156:159], v[172:175], v[116:119]
	v_mfma_f32_16x16x32_bf16 v[112:115], v[164:167], v[172:175], v[112:115]
	v_mfma_f32_16x16x32_bf16 v[100:103], v[156:159], v[180:183], v[100:103]
	v_mfma_f32_16x16x32_bf16 v[96:99], v[164:167], v[180:183], v[96:99]
	v_mfma_f32_16x16x32_bf16 v[84:87], v[156:159], v[208:211], v[84:87]
	v_mfma_f32_16x16x32_bf16 v[80:83], v[164:167], v[208:211], v[80:83]
	v_mfma_f32_16x16x32_bf16 v[68:71], v[156:159], v[216:219], v[68:71]
	v_mfma_f32_16x16x32_bf16 v[64:67], v[164:167], v[216:219], v[64:67]
	v_mfma_f32_16x16x32_bf16 v[116:119], v[160:163], v[176:179], v[116:119]
	v_mfma_f32_16x16x32_bf16 v[112:115], v[168:171], v[176:179], v[112:115]
	v_mfma_f32_16x16x32_bf16 v[100:103], v[160:163], v[204:207], v[100:103]
	v_mfma_f32_16x16x32_bf16 v[96:99], v[168:171], v[204:207], v[96:99]
	v_mfma_f32_16x16x32_bf16 v[84:87], v[160:163], v[212:215], v[84:87]
	v_mfma_f32_16x16x32_bf16 v[80:83], v[168:171], v[212:215], v[80:83]
	v_mfma_f32_16x16x32_bf16 v[68:71], v[160:163], v[220:223], v[68:71]
	v_mfma_f32_16x16x32_bf16 v[64:67], v[168:171], v[220:223], v[64:67]
	s_barrier
	s_add_u32 s98, s42, s20
	s_addc_u32 s99, s43, s21
	s_setprio 0
	s_add_i32 s56, s50, s2
	s_mov_b32 m0, s56
	ds_read_b128 v[172:175], v149 offset:16384
	ds_read_b128 v[176:179], v149 offset:17408
	ds_read_b128 v[180:183], v149 offset:18432
	ds_read_b128 v[204:207], v149 offset:19456
	ds_read_b128 v[208:211], v149 offset:20480
	ds_read_b128 v[212:215], v149 offset:21504
	ds_read_b128 v[216:219], v149 offset:22528
	ds_read_b128 v[220:223], v149 offset:23552
	global_load_lds_dwordx4 v194, s[40:41]
	s_add_i32 m0, s56, 0x2000
	s_add_u32 s56, s40, 0x4000
	s_addc_u32 s57, s41, 0
	s_add_i32 s58, s51, s2
	global_load_lds_dwordx4 v198, s[40:41]
	s_mov_b32 m0, s58
	s_nop 0
	global_load_lds_dwordx4 v194, s[56:57]
	s_add_i32 m0, s58, 0x2000
	s_nop 0
	global_load_lds_dwordx4 v198, s[56:57]
	s_waitcnt vmcnt(6)
	s_waitcnt lgkmcnt(0)
	s_setprio 1
	s_barrier
	v_mfma_f32_16x16x32_bf16 v[60:63], v[132:135], v[172:175], v[60:63]
	v_mfma_f32_16x16x32_bf16 v[56:59], v[140:143], v[172:175], v[56:59]
	v_mfma_f32_16x16x32_bf16 v[44:47], v[132:135], v[180:183], v[44:47]
	v_mfma_f32_16x16x32_bf16 v[40:43], v[140:143], v[180:183], v[40:43]
	v_mfma_f32_16x16x32_bf16 v[28:31], v[132:135], v[208:211], v[28:31]
	v_mfma_f32_16x16x32_bf16 v[24:27], v[140:143], v[208:211], v[24:27]
	v_mfma_f32_16x16x32_bf16 v[12:15], v[132:135], v[216:219], v[12:15]
	v_mfma_f32_16x16x32_bf16 v[8:11], v[140:143], v[216:219], v[8:11]
	v_mfma_f32_16x16x32_bf16 v[60:63], v[136:139], v[176:179], v[60:63]
	v_mfma_f32_16x16x32_bf16 v[56:59], v[152:155], v[176:179], v[56:59]
	v_mfma_f32_16x16x32_bf16 v[44:47], v[136:139], v[204:207], v[44:47]
	v_mfma_f32_16x16x32_bf16 v[40:43], v[152:155], v[204:207], v[40:43]
	v_mfma_f32_16x16x32_bf16 v[28:31], v[136:139], v[212:215], v[28:31]
	v_mfma_f32_16x16x32_bf16 v[24:27], v[152:155], v[212:215], v[24:27]
	v_mfma_f32_16x16x32_bf16 v[12:15], v[136:139], v[220:223], v[12:15]
	v_mfma_f32_16x16x32_bf16 v[8:11], v[152:155], v[220:223], v[8:11]
	v_mfma_f32_16x16x32_bf16 v[52:55], v[156:159], v[172:175], v[52:55]
	v_mfma_f32_16x16x32_bf16 v[48:51], v[164:167], v[172:175], v[48:51]
	v_mfma_f32_16x16x32_bf16 v[36:39], v[156:159], v[180:183], v[36:39]
	v_mfma_f32_16x16x32_bf16 v[32:35], v[164:167], v[180:183], v[32:35]
	v_mfma_f32_16x16x32_bf16 v[20:23], v[156:159], v[208:211], v[20:23]
	v_mfma_f32_16x16x32_bf16 v[16:19], v[164:167], v[208:211], v[16:19]
	v_mfma_f32_16x16x32_bf16 v[4:7], v[156:159], v[216:219], v[4:7]
	v_mfma_f32_16x16x32_bf16 v[0:3], v[164:167], v[216:219], v[0:3]
	v_mfma_f32_16x16x32_bf16 v[52:55], v[160:163], v[176:179], v[52:55]
	v_mfma_f32_16x16x32_bf16 v[48:51], v[168:171], v[176:179], v[48:51]
	v_mfma_f32_16x16x32_bf16 v[36:39], v[160:163], v[204:207], v[36:39]
	v_mfma_f32_16x16x32_bf16 v[32:35], v[168:171], v[204:207], v[32:35]
	v_mfma_f32_16x16x32_bf16 v[20:23], v[160:163], v[212:215], v[20:23]
	v_mfma_f32_16x16x32_bf16 v[16:19], v[168:171], v[212:215], v[16:19]
	v_mfma_f32_16x16x32_bf16 v[4:7], v[160:163], v[220:223], v[4:7]
	v_mfma_f32_16x16x32_bf16 v[0:3], v[168:171], v[220:223], v[0:3]
	s_barrier
; #define PG8_STAGE(bufoff, gbase, voff) do { _Pragma("unroll") for (int _i = 0; _i < 2; ++_i) \
;         __builtin_amdgcn_global_load_lds((const unsigned*)((const char*)(gbase) + (voff)[_i]), (PG8_LAS unsigned*)(lds + (bufoff) + ldsw + _i * 8192), 16, 0, 0); } while (0)
; #define PG8_LDA(dst, b, h) do { _Pragma("unroll") for (int m = 0; m < 4; ++m) _Pragma("unroll") for (int k = 0; k < 2; ++k) dst[m][k] = *(const PG8_LAS bf16x8*)(lds + PG8_SA(b, h) + aoff + m * 2048 + k * 1024); } while (0)
; #define PG8_LDB(dst, b, h) do { _Pragma("unroll") for (int n = 0; n < 2; ++n) _Pragma("unroll") for (int k = 0; k < 2; ++k) dst[n][k] = *(const PG8_LAS bf16x8*)(lds + PG8_SB(b, h) + boff + n * 2048 + k * 1024); } while (0)
; #define PG8_MMA(ai, bj, At, Bt) do { __builtin_amdgcn_s_setprio(1); _Pragma("unroll") for (int m = 0; m < 4; ++m) _Pragma("unroll") for (int n = 0; n < 2; ++n) _Pragma("unroll") for (int k = 0; k < 2; ++k) \
;         acc[ai][bj][m][n] = __builtin_amdgcn_mfma_f32_16x16x32_bf16(Bt[n][k], At[m][k], acc[ai][bj][m][n], 0, 0, 0); __builtin_amdgcn_s_setprio(0); } while (0)
; #define PG8_WAIT_V(n) asm volatile("s_waitcnt vmcnt(" #n ")" ::: "memory")
; #define PG8_WAIT_L(n) asm volatile("s_waitcnt lgkmcnt(" #n ")" ::: "memory")
; #define PG8_BAR __builtin_amdgcn_s_barrier()
; #define PG8_SCHED __builtin_amdgcn_sched_barrier(0)
; template <class Epi, class Sched, bool ALIGN_EPI = false, bool SP2 = false>
; __device__ __forceinline__ void gemm_phase(PG8_LAS unsigned char* lds, const Gemm g, const Sched& S, const Epi& E) {
;     ...
;             PG8_LDB(B0, 1, 0); PG8_LDB(B1, 1, 1); PG8_SCHED; PG8_LDA(At, 1, 0); PG8_STAGE(PG8_SA(0, 1), a2 + hstepA, voffA);
;             PG8_WAIT_V(8); PG8_WAIT_L(0); PG8_BAR; PG8_MMA(0, 0, At, B0); PG8_MMA(0, 1, At, B1); PG8_BAR; PG8_SCHED;
;             PG8_LDA(At, 1, 1); PG8_STAGE(PG8_SB(1, 0), b3, voffB); PG8_STAGE(PG8_SB(1, 1), b3 + hstepB, voffB); PG8_STAGE(PG8_SA(1, 0), a3, voffA);
;             PG8_WAIT_V(8); PG8_WAIT_L(0); PG8_BAR; PG8_MMA(1, 0, At, B0); PG8_MMA(1, 1, At, B1); PG8_BAR; PG8_SCHED;
	s_setprio 0
	s_add_i32 s56, 0, 0x18000
	v_add_u32_e32 v151, s56, v145
	s_add_i32 s57, 0, 0x1c000
	ds_read_b128 v[132:135], v151
	ds_read_b128 v[136:139], v151 offset:1024
	ds_read_b128 v[140:143], v151 offset:2048
	ds_read_b128 v[152:155], v151 offset:3072
	v_add_u32_e32 v151, s57, v145
	ds_read_b128 v[156:159], v151
	ds_read_b128 v[160:163], v151 offset:1024
	ds_read_b128 v[164:167], v151 offset:2048
	ds_read_b128 v[168:171], v151 offset:3072
	s_mov_b32 m0, s13
	s_nop 0
	global_load_lds_dwordx4 v192, s[42:43]
	s_mov_b32 m0, s14
	s_nop 0
	global_load_lds_dwordx4 v196, s[42:43]
	s_add_u32 s42, s42, 0x80000
	s_addc_u32 s43, s43, 0
	s_mov_b32 m0, s15
	ds_read_b128 v[172:175], v149 offset:32768
	ds_read_b128 v[176:179], v149 offset:33792
	ds_read_b128 v[180:183], v149 offset:34816
	ds_read_b128 v[204:207], v149 offset:35840
	ds_read_b128 v[208:211], v149 offset:36864
	ds_read_b128 v[212:215], v149 offset:37888
	ds_read_b128 v[216:219], v149 offset:38912
	ds_read_b128 v[220:223], v149 offset:39936
	global_load_lds_dwordx4 v192, s[42:43]
	s_mov_b32 m0, s44
	s_nop 0
	global_load_lds_dwordx4 v196, s[42:43]
	s_waitcnt vmcnt(8)
	s_waitcnt lgkmcnt(0)
	s_setprio 1
	s_barrier
	v_mfma_f32_16x16x32_bf16 v[124:127], v[132:135], v[172:175], v[124:127]
	v_mfma_f32_16x16x32_bf16 v[120:123], v[140:143], v[172:175], v[120:123]
	v_mfma_f32_16x16x32_bf16 v[108:111], v[132:135], v[180:183], v[108:111]
	v_mfma_f32_16x16x32_bf16 v[104:107], v[140:143], v[180:183], v[104:107]
	v_mfma_f32_16x16x32_bf16 v[92:95], v[132:135], v[208:211], v[92:95]
	v_mfma_f32_16x16x32_bf16 v[88:91], v[140:143], v[208:211], v[88:91]
	v_mfma_f32_16x16x32_bf16 v[76:79], v[132:135], v[216:219], v[76:79]
	v_mfma_f32_16x16x32_bf16 v[72:75], v[140:143], v[216:219], v[72:75]
	v_mfma_f32_16x16x32_bf16 v[124:127], v[136:139], v[176:179], v[124:127]
	v_mfma_f32_16x16x32_bf16 v[120:123], v[152:155], v[176:179], v[120:123]
	v_mfma_f32_16x16x32_bf16 v[108:111], v[136:139], v[204:207], v[108:111]
	v_mfma_f32_16x16x32_bf16 v[104:107], v[152:155], v[204:207], v[104:107]
	v_mfma_f32_16x16x32_bf16 v[92:95], v[136:139], v[212:215], v[92:95]
	v_mfma_f32_16x16x32_bf16 v[88:91], v[152:155], v[212:215], v[88:91]
	v_mfma_f32_16x16x32_bf16 v[76:79], v[136:139], v[220:223], v[76:79]
	v_mfma_f32_16x16x32_bf16 v[72:75], v[152:155], v[220:223], v[72:75]
	v_mfma_f32_16x16x32_bf16 v[116:119], v[156:159], v[172:175], v[116:119]
	v_mfma_f32_16x16x32_bf16 v[112:115], v[164:167], v[172:175], v[112:115]
	v_mfma_f32_16x16x32_bf16 v[100:103], v[156:159], v[180:183], v[100:103]
	v_mfma_f32_16x16x32_bf16 v[96:99], v[164:167], v[180:183], v[96:99]
	v_mfma_f32_16x16x32_bf16 v[84:87], v[156:159], v[208:211], v[84:87]
	v_mfma_f32_16x16x32_bf16 v[80:83], v[164:167], v[208:211], v[80:83]
	v_mfma_f32_16x16x32_bf16 v[68:71], v[156:159], v[216:219], v[68:71]
	v_mfma_f32_16x16x32_bf16 v[64:67], v[164:167], v[216:219], v[64:67]
	v_mfma_f32_16x16x32_bf16 v[116:119], v[160:163], v[176:179], v[116:119]
	v_mfma_f32_16x16x32_bf16 v[112:115], v[168:171], v[176:179], v[112:115]
	v_mfma_f32_16x16x32_bf16 v[100:103], v[160:163], v[204:207], v[100:103]
	v_mfma_f32_16x16x32_bf16 v[96:99], v[168:171], v[204:207], v[96:99]
	v_mfma_f32_16x16x32_bf16 v[84:87], v[160:163], v[212:215], v[84:87]
	v_mfma_f32_16x16x32_bf16 v[80:83], v[168:171], v[212:215], v[80:83]
	v_mfma_f32_16x16x32_bf16 v[68:71], v[160:163], v[220:223], v[68:71]
	v_mfma_f32_16x16x32_bf16 v[64:67], v[168:171], v[220:223], v[64:67]
	s_barrier
	s_setprio 0
	s_add_u32 s42, s40, 0x8000
	s_addc_u32 s43, s41, 0
	s_add_i32 s56, s56, s2
	s_mov_b32 m0, s56
	ds_read_b128 v[172:175], v149 offset:49152
	ds_read_b128 v[176:179], v149 offset:50176
	ds_read_b128 v[180:183], v149 offset:51200
	ds_read_b128 v[204:207], v149 offset:52224
	ds_read_b128 v[208:211], v149 offset:53248
	ds_read_b128 v[212:215], v149 offset:54272
	ds_read_b128 v[216:219], v149 offset:55296
	ds_read_b128 v[220:223], v149 offset:56320
	global_load_lds_dwordx4 v194, s[42:43]
	s_add_i32 m0, s56, 0x2000
	s_add_u32 s40, s40, 0xc000
	s_addc_u32 s41, s41, 0
	global_load_lds_dwordx4 v198, s[42:43]
	s_add_i32 s42, s57, s2
	s_mov_b32 m0, s42
	s_nop 0
	global_load_lds_dwordx4 v194, s[40:41]
	s_add_i32 m0, s42, 0x2000
	s_nop 0
	global_load_lds_dwordx4 v198, s[40:41]
	s_waitcnt vmcnt(6)
	s_waitcnt lgkmcnt(0)
	s_setprio 1
	s_barrier
	v_mfma_f32_16x16x32_bf16 v[60:63], v[132:135], v[172:175], v[60:63]
	v_mfma_f32_16x16x32_bf16 v[56:59], v[140:143], v[172:175], v[56:59]
	v_mfma_f32_16x16x32_bf16 v[44:47], v[132:135], v[180:183], v[44:47]
	v_mfma_f32_16x16x32_bf16 v[40:43], v[140:143], v[180:183], v[40:43]
	v_mfma_f32_16x16x32_bf16 v[28:31], v[132:135], v[208:211], v[28:31]
	v_mfma_f32_16x16x32_bf16 v[24:27], v[140:143], v[208:211], v[24:27]
	v_mfma_f32_16x16x32_bf16 v[12:15], v[132:135], v[216:219], v[12:15]
	v_mfma_f32_16x16x32_bf16 v[8:11], v[140:143], v[216:219], v[8:11]
	v_mfma_f32_16x16x32_bf16 v[60:63], v[136:139], v[176:179], v[60:63]
	v_mfma_f32_16x16x32_bf16 v[56:59], v[152:155], v[176:179], v[56:59]
	v_mfma_f32_16x16x32_bf16 v[44:47], v[136:139], v[204:207], v[44:47]
	v_mfma_f32_16x16x32_bf16 v[40:43], v[152:155], v[204:207], v[40:43]
	v_mfma_f32_16x16x32_bf16 v[28:31], v[136:139], v[212:215], v[28:31]
	v_mfma_f32_16x16x32_bf16 v[24:27], v[152:155], v[212:215], v[24:27]
	v_mfma_f32_16x16x32_bf16 v[12:15], v[136:139], v[220:223], v[12:15]
	v_mfma_f32_16x16x32_bf16 v[8:11], v[152:155], v[220:223], v[8:11]
	v_mfma_f32_16x16x32_bf16 v[52:55], v[156:159], v[172:175], v[52:55]
	v_mfma_f32_16x16x32_bf16 v[48:51], v[164:167], v[172:175], v[48:51]
	v_mfma_f32_16x16x32_bf16 v[36:39], v[156:159], v[180:183], v[36:39]
	v_mfma_f32_16x16x32_bf16 v[32:35], v[164:167], v[180:183], v[32:35]
	v_mfma_f32_16x16x32_bf16 v[20:23], v[156:159], v[208:211], v[20:23]
	v_mfma_f32_16x16x32_bf16 v[16:19], v[164:167], v[208:211], v[16:19]
	v_mfma_f32_16x16x32_bf16 v[4:7], v[156:159], v[216:219], v[4:7]
	v_mfma_f32_16x16x32_bf16 v[0:3], v[164:167], v[216:219], v[0:3]
	v_mfma_f32_16x16x32_bf16 v[52:55], v[160:163], v[176:179], v[52:55]
	v_mfma_f32_16x16x32_bf16 v[48:51], v[168:171], v[176:179], v[48:51]
	v_mfma_f32_16x16x32_bf16 v[36:39], v[160:163], v[204:207], v[36:39]
	v_mfma_f32_16x16x32_bf16 v[32:35], v[168:171], v[204:207], v[32:35]
	v_mfma_f32_16x16x32_bf16 v[20:23], v[160:163], v[212:215], v[20:23]
	v_mfma_f32_16x16x32_bf16 v[16:19], v[168:171], v[212:215], v[16:19]
	v_mfma_f32_16x16x32_bf16 v[4:7], v[160:163], v[220:223], v[4:7]
	v_mfma_f32_16x16x32_bf16 v[0:3], v[168:171], v[220:223], v[0:3]
	s_barrier
	s_setprio 0
	s_add_i32 s55, s55, 2
	s_add_u32 s53, s53, 0x10000
	s_addc_u32 s54, s54, 0
	s_add_u32 s38, s38, 0x100
	s_addc_u32 s39, s39, 0
	s_cmp_gt_u32 s55, 29
	s_cbranch_scc0 .LBB0_616
	s_and_b64 vcc, exec, s[22:23]
	s_cbranch_vccz .LBB0_619
	s_barrier

; #define PG8_STAGE(bufoff, gbase, voff) do { _Pragma("unroll") for (int _i = 0; _i < 2; ++_i) \
;         __builtin_amdgcn_global_load_lds((const unsigned*)((const char*)(gbase) + (voff)[_i]), (PG8_LAS unsigned*)(lds + (bufoff) + ldsw + _i * 8192), 16, 0, 0); } while (0)
; #define PG8_LDA(dst, b, h) do { _Pragma("unroll") for (int m = 0; m < 4; ++m) _Pragma("unroll") for (int k = 0; k < 2; ++k) dst[m][k] = *(const PG8_LAS bf16x8*)(lds + PG8_SA(b, h) + aoff + m * 2048 + k * 1024); } while (0)
; #define PG8_LDB(dst, b, h) do { _Pragma("unroll") for (int n = 0; n < 2; ++n) _Pragma("unroll") for (int k = 0; k < 2; ++k) dst[n][k] = *(const PG8_LAS bf16x8*)(lds + PG8_SB(b, h) + boff + n * 2048 + k * 1024); } while (0)
; #define PG8_WAIT_V(n) asm volatile("s_waitcnt vmcnt(" #n ")" ::: "memory")
; #define PG8_WAIT_L(n) asm volatile("s_waitcnt lgkmcnt(" #n ")" ::: "memory")
; #define PG8_BAR __builtin_amdgcn_s_barrier()
; template <class Epi, class Sched, bool ALIGN_EPI = false, bool SP2 = false>
; __device__ __forceinline__ void gemm_phase(PG8_LAS unsigned char* lds, const Gemm g, const Sched& S, const Epi& E) {
;     ...
;         const bool has_next = S.next(ui + 1, nxt);
;         const char* nA = has_next ? (const char*)g.A + (size_t)nxt.pm * tstep + (size_t)nxt.k0 * kstepA : cA; const char* nB = has_next ? (const char*)g.Bt + (size_t)nxt.pn * tstep + (size_t)nxt.k0 * kstepB : cB;
;         for (int t = 0; t < nt; t += 2) {
;             const bool last = (t == nt - 2);
;             const char* a1 = cA + (size_t)(t + 1) * kstepA;
;             const char* a2 = last ? nA : cA + (size_t)(t + 2) * kstepA; const char* b2 = last ? nB : cB + (size_t)(t + 2) * kstepB;
;             const char* a3 = a2 + kstepA; const char* b3 = b2 + kstepB;
;             if (last && has_next) S.a_ready(nxt);
;             if constexpr (SP2) {
;             PG8_LDB(B0, 0, 0); PG8_LDB(B1, 0, 1); PG8_SCHED; PG8_LDA(At, 0, 0); PG8_STAGE(PG8_SA(1, 1), a1 + hstepA, voffA);
;             PG8_WAIT_V(8); PG8_WAIT_L(0); PG8_BAR; PG8_MMA(0, 0, At, B0); PG8_MMA(0, 1, At, B1); PG8_BAR; PG8_SCHED;
;             PG8_LDA(At, 0, 1); PG8_STAGE(PG8_SB(0, 0), b2, voffB); PG8_STAGE(PG8_SB(0, 1), b2 + hstepB, voffB); PG8_STAGE(PG8_SA(0, 0), a2, voffA);
;             PG8_WAIT_V(8); PG8_WAIT_L(0); PG8_BAR; PG8_MMA(1, 0, At, B0); PG8_MMA(1, 1, At, B1); PG8_BAR; PG8_SCHED;
.LBB0_938:
	s_sub_u32 s100, s46, 0x40000
	s_subb_u32 s101, s47, 0
	s_add_i32 s71, s48, 2
	s_add_u32 s49, s46, 0xfffc0080
	s_addc_u32 s50, s47, -1
	s_add_i32 s72, 0, 0x10000
	s_cmp_eq_u32 s68, s48
	s_cselect_b32 s51, s1, s50
	s_cselect_b32 s50, s31, s49
	s_cselect_b32 s49, s35, s70
	s_cselect_b32 s48, s37, s69
	s_add_i32 s74, 0, 0x14000
	v_add_u32_e32 v140, s72, v247
	v_add_u32_e32 v156, s74, v247
	ds_read_b128 v[128:131], v140
	ds_read_b128 v[132:135], v140 offset:1024
	ds_read_b128 v[136:139], v140 offset:2048
	ds_read_b128 v[140:143], v140 offset:3072
	ds_read_b128 v[144:147], v156
	ds_read_b128 v[148:151], v156 offset:1024
	ds_read_b128 v[152:155], v156 offset:2048
	ds_read_b128 v[156:159], v156 offset:3072
	ds_read_b128 v[160:163], v249
	ds_read_b128 v[164:167], v249 offset:1024
	ds_read_b128 v[168:171], v249 offset:2048
	ds_read_b128 v[172:175], v249 offset:3072
	ds_read_b128 v[176:179], v249 offset:4096
	ds_read_b128 v[180:183], v249 offset:5120
	ds_read_b128 v[184:187], v249 offset:6144
	ds_read_b128 v[188:191], v249 offset:7168
	s_mov_b32 m0, s62
	s_nop 0
	global_load_lds_dwordx4 v212, s[100:101]
	s_mov_b32 m0, s63
	s_nop 0
	global_load_lds_dwordx4 v214, s[100:101]
	s_add_i32 m0, s45, 0xc000
	s_nop 0
	global_load_lds_dwordx4 v212, s[46:47]
	s_add_i32 m0, s45, 0xe000
	s_nop 0
	global_load_lds_dwordx4 v214, s[46:47]
	s_waitcnt vmcnt(8)
	s_waitcnt lgkmcnt(0)
	s_setprio 1
	s_barrier
	v_mfma_f32_16x16x32_bf16 v[124:127], v[128:131], v[160:163], v[124:127]
	v_mfma_f32_16x16x32_bf16 v[120:123], v[136:139], v[160:163], v[120:123]
	v_mfma_f32_16x16x32_bf16 v[112:115], v[128:131], v[168:171], v[112:115]
	v_mfma_f32_16x16x32_bf16 v[104:107], v[136:139], v[168:171], v[104:107]
	v_mfma_f32_16x16x32_bf16 v[96:99], v[128:131], v[176:179], v[96:99]
	v_mfma_f32_16x16x32_bf16 v[88:91], v[136:139], v[176:179], v[88:91]
	v_mfma_f32_16x16x32_bf16 v[80:83], v[128:131], v[184:187], v[80:83]
	v_mfma_f32_16x16x32_bf16 v[72:75], v[136:139], v[184:187], v[72:75]
	v_mfma_f32_16x16x32_bf16 v[124:127], v[132:135], v[164:167], v[124:127]
	v_mfma_f32_16x16x32_bf16 v[120:123], v[140:143], v[164:167], v[120:123]
	v_mfma_f32_16x16x32_bf16 v[112:115], v[132:135], v[172:175], v[112:115]
	v_mfma_f32_16x16x32_bf16 v[104:107], v[140:143], v[172:175], v[104:107]
	v_mfma_f32_16x16x32_bf16 v[96:99], v[132:135], v[180:183], v[96:99]
	v_mfma_f32_16x16x32_bf16 v[88:91], v[140:143], v[180:183], v[88:91]
	v_mfma_f32_16x16x32_bf16 v[80:83], v[132:135], v[188:191], v[80:83]
	v_mfma_f32_16x16x32_bf16 v[72:75], v[140:143], v[188:191], v[72:75]
	v_mfma_f32_16x16x32_bf16 v[116:119], v[144:147], v[160:163], v[116:119]
	v_mfma_f32_16x16x32_bf16 v[108:111], v[152:155], v[160:163], v[108:111]
	v_mfma_f32_16x16x32_bf16 v[100:103], v[144:147], v[168:171], v[100:103]
	v_mfma_f32_16x16x32_bf16 v[92:95], v[152:155], v[168:171], v[92:95]
	v_mfma_f32_16x16x32_bf16 v[84:87], v[144:147], v[176:179], v[84:87]
	v_mfma_f32_16x16x32_bf16 v[76:79], v[152:155], v[176:179], v[76:79]
	v_mfma_f32_16x16x32_bf16 v[68:71], v[144:147], v[184:187], v[68:71]
	v_mfma_f32_16x16x32_bf16 v[64:67], v[152:155], v[184:187], v[64:67]
	v_mfma_f32_16x16x32_bf16 v[116:119], v[148:151], v[164:167], v[116:119]
	v_mfma_f32_16x16x32_bf16 v[108:111], v[156:159], v[164:167], v[108:111]
	v_mfma_f32_16x16x32_bf16 v[100:103], v[148:151], v[172:175], v[100:103]
	v_mfma_f32_16x16x32_bf16 v[92:95], v[156:159], v[172:175], v[92:95]
	v_mfma_f32_16x16x32_bf16 v[84:87], v[148:151], v[180:183], v[84:87]
	v_mfma_f32_16x16x32_bf16 v[76:79], v[156:159], v[180:183], v[76:79]
	v_mfma_f32_16x16x32_bf16 v[68:71], v[148:151], v[188:191], v[68:71]
	v_mfma_f32_16x16x32_bf16 v[64:67], v[156:159], v[188:191], v[64:67]
	s_barrier
	s_add_u32 s98, s48, s20
	s_addc_u32 s99, s49, s21
	s_add_u32 s100, s50, s20
	s_addc_u32 s101, s51, s21
	s_setprio 0
	s_add_i32 s72, s72, s56
	s_mov_b32 m0, s72
	ds_read_b128 v[160:163], v249 offset:16384
	ds_read_b128 v[164:167], v249 offset:17408
	ds_read_b128 v[168:171], v249 offset:18432
	ds_read_b128 v[172:175], v249 offset:19456
	ds_read_b128 v[176:179], v249 offset:20480
	ds_read_b128 v[180:183], v249 offset:21504
	ds_read_b128 v[184:187], v249 offset:22528
	ds_read_b128 v[188:191], v249 offset:23552
	global_load_lds_dwordx4 v206, s[48:49]
	s_add_i32 m0, s72, 0x2000
	s_add_u32 s72, s48, 0x40000
	s_addc_u32 s73, s49, 0
	s_add_i32 s74, s74, s56
	global_load_lds_dwordx4 v210, s[48:49]
	s_mov_b32 m0, s74
	s_nop 0
	global_load_lds_dwordx4 v206, s[72:73]
	s_add_i32 m0, s74, 0x2000
	s_nop 0
	global_load_lds_dwordx4 v210, s[72:73]
	s_waitcnt vmcnt(6)
	s_waitcnt lgkmcnt(0)
	s_setprio 1
	s_barrier
; #define PG8_STAGE(bufoff, gbase, voff) do { _Pragma("unroll") for (int _i = 0; _i < 2; ++_i) \
;         __builtin_amdgcn_global_load_lds((const unsigned*)((const char*)(gbase) + (voff)[_i]), (PG8_LAS unsigned*)(lds + (bufoff) + ldsw + _i * 8192), 16, 0, 0); } while (0)
; #define PG8_LDA(dst, b, h) do { _Pragma("unroll") for (int m = 0; m < 4; ++m) _Pragma("unroll") for (int k = 0; k < 2; ++k) dst[m][k] = *(const PG8_LAS bf16x8*)(lds + PG8_SA(b, h) + aoff + m * 2048 + k * 1024); } while (0)
; #define PG8_LDB(dst, b, h) do { _Pragma("unroll") for (int n = 0; n < 2; ++n) _Pragma("unroll") for (int k = 0; k < 2; ++k) dst[n][k] = *(const PG8_LAS bf16x8*)(lds + PG8_SB(b, h) + boff + n * 2048 + k * 1024); } while (0)
; #define PG8_MMA(ai, bj, At, Bt) do { __builtin_amdgcn_s_setprio(1); _Pragma("unroll") for (int m = 0; m < 4; ++m) _Pragma("unroll") for (int n = 0; n < 2; ++n) _Pragma("unroll") for (int k = 0; k < 2; ++k) \
;         acc[ai][bj][m][n] = __builtin_amdgcn_mfma_f32_16x16x32_bf16(Bt[n][k], At[m][k], acc[ai][bj][m][n], 0, 0, 0); __builtin_amdgcn_s_setprio(0); } while (0)
; #define PG8_WAIT_V(n) asm volatile("s_waitcnt vmcnt(" #n ")" ::: "memory")
; #define PG8_WAIT_L(n) asm volatile("s_waitcnt lgkmcnt(" #n ")" ::: "memory")
; #define PG8_BAR __builtin_amdgcn_s_barrier()
; #define PG8_SCHED __builtin_amdgcn_sched_barrier(0)
; template <class Epi, class Sched, bool ALIGN_EPI = false, bool SP2 = false>
; __device__ __forceinline__ void gemm_phase(PG8_LAS unsigned char* lds, const Gemm g, const Sched& S, const Epi& E) {
;     ...
;             PG8_WAIT_V(8); PG8_WAIT_L(0); PG8_BAR; PG8_MMA(1, 0, At, B0); PG8_MMA(1, 1, At, B1); PG8_BAR; PG8_SCHED;
;             PG8_LDB(B0, 1, 0); PG8_LDB(B1, 1, 1); PG8_SCHED; PG8_LDA(At, 1, 0); PG8_STAGE(PG8_SA(0, 1), a2 + hstepA, voffA);
;             PG8_WAIT_V(8); PG8_WAIT_L(0); PG8_BAR; PG8_MMA(0, 0, At, B0); PG8_MMA(0, 1, At, B1); PG8_BAR; PG8_SCHED;
	v_mfma_f32_16x16x32_bf16 v[60:63], v[128:131], v[160:163], v[60:63]
	v_mfma_f32_16x16x32_bf16 v[56:59], v[136:139], v[160:163], v[56:59]
	v_mfma_f32_16x16x32_bf16 v[48:51], v[128:131], v[168:171], v[48:51]
	v_mfma_f32_16x16x32_bf16 v[40:43], v[136:139], v[168:171], v[40:43]
	v_mfma_f32_16x16x32_bf16 v[32:35], v[128:131], v[176:179], v[32:35]
	v_mfma_f32_16x16x32_bf16 v[24:27], v[136:139], v[176:179], v[24:27]
	v_mfma_f32_16x16x32_bf16 v[16:19], v[128:131], v[184:187], v[16:19]
	v_mfma_f32_16x16x32_bf16 v[8:11], v[136:139], v[184:187], v[8:11]
	v_mfma_f32_16x16x32_bf16 v[60:63], v[132:135], v[164:167], v[60:63]
	v_mfma_f32_16x16x32_bf16 v[56:59], v[140:143], v[164:167], v[56:59]
	v_mfma_f32_16x16x32_bf16 v[48:51], v[132:135], v[172:175], v[48:51]
	v_mfma_f32_16x16x32_bf16 v[40:43], v[140:143], v[172:175], v[40:43]
	v_mfma_f32_16x16x32_bf16 v[32:35], v[132:135], v[180:183], v[32:35]
	v_mfma_f32_16x16x32_bf16 v[24:27], v[140:143], v[180:183], v[24:27]
	v_mfma_f32_16x16x32_bf16 v[16:19], v[132:135], v[188:191], v[16:19]
	v_mfma_f32_16x16x32_bf16 v[8:11], v[140:143], v[188:191], v[8:11]
	v_mfma_f32_16x16x32_bf16 v[52:55], v[144:147], v[160:163], v[52:55]
	v_mfma_f32_16x16x32_bf16 v[44:47], v[152:155], v[160:163], v[44:47]
	v_mfma_f32_16x16x32_bf16 v[36:39], v[144:147], v[168:171], v[36:39]
	v_mfma_f32_16x16x32_bf16 v[28:31], v[152:155], v[168:171], v[28:31]
	v_mfma_f32_16x16x32_bf16 v[20:23], v[144:147], v[176:179], v[20:23]
	v_mfma_f32_16x16x32_bf16 v[12:15], v[152:155], v[176:179], v[12:15]
	v_mfma_f32_16x16x32_bf16 v[4:7], v[144:147], v[184:187], v[4:7]
	v_mfma_f32_16x16x32_bf16 v[0:3], v[152:155], v[184:187], v[0:3]
	v_mfma_f32_16x16x32_bf16 v[52:55], v[148:151], v[164:167], v[52:55]
	v_mfma_f32_16x16x32_bf16 v[44:47], v[156:159], v[164:167], v[44:47]
	v_mfma_f32_16x16x32_bf16 v[36:39], v[148:151], v[172:175], v[36:39]
	v_mfma_f32_16x16x32_bf16 v[28:31], v[156:159], v[172:175], v[28:31]
	v_mfma_f32_16x16x32_bf16 v[20:23], v[148:151], v[180:183], v[20:23]
	v_mfma_f32_16x16x32_bf16 v[12:15], v[156:159], v[180:183], v[12:15]
	v_mfma_f32_16x16x32_bf16 v[4:7], v[148:151], v[188:191], v[4:7]
	v_mfma_f32_16x16x32_bf16 v[0:3], v[156:159], v[188:191], v[0:3]
	s_barrier
	s_setprio 0
	s_add_i32 s72, 0, 0x18000
	s_add_i32 s73, 0, 0x1c000
	v_add_u32_e32 v140, s72, v247
	v_add_u32_e32 v156, s73, v247
	ds_read_b128 v[128:131], v140
	ds_read_b128 v[132:135], v140 offset:1024
	ds_read_b128 v[136:139], v140 offset:2048
	ds_read_b128 v[140:143], v140 offset:3072
	ds_read_b128 v[144:147], v156
	ds_read_b128 v[148:151], v156 offset:1024
	ds_read_b128 v[152:155], v156 offset:2048
	ds_read_b128 v[156:159], v156 offset:3072
	s_mov_b32 m0, s45
	s_nop 0
	global_load_lds_dwordx4 v204, s[50:51]
	s_mov_b32 m0, s57
	s_nop 0
	global_load_lds_dwordx4 v208, s[50:51]
	s_add_u32 s50, s50, 0x40000
	s_addc_u32 s51, s51, 0
	s_mov_b32 m0, s58
	ds_read_b128 v[160:163], v249 offset:32768
	ds_read_b128 v[164:167], v249 offset:33792
	ds_read_b128 v[168:171], v249 offset:34816
	ds_read_b128 v[172:175], v249 offset:35840
	ds_read_b128 v[176:179], v249 offset:36864
	ds_read_b128 v[180:183], v249 offset:37888
	ds_read_b128 v[184:187], v249 offset:38912
	ds_read_b128 v[188:191], v249 offset:39936
	global_load_lds_dwordx4 v204, s[50:51]
	s_mov_b32 m0, s59
	s_nop 0
	global_load_lds_dwordx4 v208, s[50:51]
	s_waitcnt vmcnt(8)
	s_waitcnt lgkmcnt(0)
	s_setprio 1
	s_barrier
; #define PG8_STAGE(bufoff, gbase, voff) do { _Pragma("unroll") for (int _i = 0; _i < 2; ++_i) \
;         __builtin_amdgcn_global_load_lds((const unsigned*)((const char*)(gbase) + (voff)[_i]), (PG8_LAS unsigned*)(lds + (bufoff) + ldsw + _i * 8192), 16, 0, 0); } while (0)
; #define PG8_LDA(dst, b, h) do { _Pragma("unroll") for (int m = 0; m < 4; ++m) _Pragma("unroll") for (int k = 0; k < 2; ++k) dst[m][k] = *(const PG8_LAS bf16x8*)(lds + PG8_SA(b, h) + aoff + m * 2048 + k * 1024); } while (0)
; #define PG8_MMA(ai, bj, At, Bt) do { __builtin_amdgcn_s_setprio(1); _Pragma("unroll") for (int m = 0; m < 4; ++m) _Pragma("unroll") for (int n = 0; n < 2; ++n) _Pragma("unroll") for (int k = 0; k < 2; ++k) \
;         acc[ai][bj][m][n] = __builtin_amdgcn_mfma_f32_16x16x32_bf16(Bt[n][k], At[m][k], acc[ai][bj][m][n], 0, 0, 0); __builtin_amdgcn_s_setprio(0); } while (0)
; #define PG8_WAIT_V(n) asm volatile("s_waitcnt vmcnt(" #n ")" ::: "memory")
; #define PG8_WAIT_L(n) asm volatile("s_waitcnt lgkmcnt(" #n ")" ::: "memory")
; #define PG8_BAR __builtin_amdgcn_s_barrier()
; #define PG8_SCHED __builtin_amdgcn_sched_barrier(0)
; template <class Epi, class Sched, bool ALIGN_EPI = false, bool SP2 = false>
; __device__ __forceinline__ void gemm_phase(PG8_LAS unsigned char* lds, const Gemm g, const Sched& S, const Epi& E) {
;     ...
;             PG8_WAIT_V(8); PG8_WAIT_L(0); PG8_BAR; PG8_MMA(0, 0, At, B0); PG8_MMA(0, 1, At, B1); PG8_BAR; PG8_SCHED;
;             PG8_LDA(At, 1, 1); PG8_STAGE(PG8_SB(1, 0), b3, voffB); PG8_STAGE(PG8_SB(1, 1), b3 + hstepB, voffB); PG8_STAGE(PG8_SA(1, 0), a3, voffA);
;             PG8_WAIT_V(8); PG8_WAIT_L(0); PG8_BAR; PG8_MMA(1, 0, At, B0); PG8_MMA(1, 1, At, B1); PG8_BAR; PG8_SCHED;
	v_mfma_f32_16x16x32_bf16 v[124:127], v[128:131], v[160:163], v[124:127]
	v_mfma_f32_16x16x32_bf16 v[120:123], v[136:139], v[160:163], v[120:123]
	v_mfma_f32_16x16x32_bf16 v[112:115], v[128:131], v[168:171], v[112:115]
	v_mfma_f32_16x16x32_bf16 v[104:107], v[136:139], v[168:171], v[104:107]
	v_mfma_f32_16x16x32_bf16 v[96:99], v[128:131], v[176:179], v[96:99]
	v_mfma_f32_16x16x32_bf16 v[88:91], v[136:139], v[176:179], v[88:91]
	v_mfma_f32_16x16x32_bf16 v[80:83], v[128:131], v[184:187], v[80:83]
	v_mfma_f32_16x16x32_bf16 v[72:75], v[136:139], v[184:187], v[72:75]
	v_mfma_f32_16x16x32_bf16 v[124:127], v[132:135], v[164:167], v[124:127]
	v_mfma_f32_16x16x32_bf16 v[120:123], v[140:143], v[164:167], v[120:123]
	v_mfma_f32_16x16x32_bf16 v[112:115], v[132:135], v[172:175], v[112:115]
	v_mfma_f32_16x16x32_bf16 v[104:107], v[140:143], v[172:175], v[104:107]
	v_mfma_f32_16x16x32_bf16 v[96:99], v[132:135], v[180:183], v[96:99]
	v_mfma_f32_16x16x32_bf16 v[88:91], v[140:143], v[180:183], v[88:91]
	v_mfma_f32_16x16x32_bf16 v[80:83], v[132:135], v[188:191], v[80:83]
	v_mfma_f32_16x16x32_bf16 v[72:75], v[140:143], v[188:191], v[72:75]
	v_mfma_f32_16x16x32_bf16 v[116:119], v[144:147], v[160:163], v[116:119]
	v_mfma_f32_16x16x32_bf16 v[108:111], v[152:155], v[160:163], v[108:111]
	v_mfma_f32_16x16x32_bf16 v[100:103], v[144:147], v[168:171], v[100:103]
	v_mfma_f32_16x16x32_bf16 v[92:95], v[152:155], v[168:171], v[92:95]
	v_mfma_f32_16x16x32_bf16 v[84:87], v[144:147], v[176:179], v[84:87]
	v_mfma_f32_16x16x32_bf16 v[76:79], v[152:155], v[176:179], v[76:79]
	v_mfma_f32_16x16x32_bf16 v[68:71], v[144:147], v[184:187], v[68:71]
	v_mfma_f32_16x16x32_bf16 v[64:67], v[152:155], v[184:187], v[64:67]
	v_mfma_f32_16x16x32_bf16 v[116:119], v[148:151], v[164:167], v[116:119]
	v_mfma_f32_16x16x32_bf16 v[108:111], v[156:159], v[164:167], v[108:111]
	v_mfma_f32_16x16x32_bf16 v[100:103], v[148:151], v[172:175], v[100:103]
	v_mfma_f32_16x16x32_bf16 v[92:95], v[156:159], v[172:175], v[92:95]
	v_mfma_f32_16x16x32_bf16 v[84:87], v[148:151], v[180:183], v[84:87]
	v_mfma_f32_16x16x32_bf16 v[76:79], v[156:159], v[180:183], v[76:79]
	v_mfma_f32_16x16x32_bf16 v[68:71], v[148:151], v[188:191], v[68:71]
	v_mfma_f32_16x16x32_bf16 v[64:67], v[156:159], v[188:191], v[64:67]
	s_barrier
	s_setprio 0
	s_add_i32 s50, s72, s56
	s_mov_b32 m0, s50
	ds_read_b128 v[160:163], v249 offset:49152
	ds_read_b128 v[164:167], v249 offset:50176
	ds_read_b128 v[168:171], v249 offset:51200
	ds_read_b128 v[172:175], v249 offset:52224
	ds_read_b128 v[176:179], v249 offset:53248
	ds_read_b128 v[180:183], v249 offset:54272
	ds_read_b128 v[184:187], v249 offset:55296
	ds_read_b128 v[188:191], v249 offset:56320
	global_load_lds_dwordx4 v206, s[98:99]
	s_add_i32 m0, s50, 0x2000
	s_add_u32 s48, s48, 0x40080
	s_addc_u32 s49, s49, 0
	s_add_i32 s50, s73, s56
	global_load_lds_dwordx4 v210, s[98:99]
	s_mov_b32 m0, s50
	s_nop 0
	global_load_lds_dwordx4 v206, s[48:49]
	s_add_i32 m0, s50, 0x2000
	s_nop 0
	global_load_lds_dwordx4 v210, s[48:49]
	s_waitcnt vmcnt(6)
	s_waitcnt lgkmcnt(0)
	s_setprio 1
	s_barrier
	v_mfma_f32_16x16x32_bf16 v[60:63], v[128:131], v[160:163], v[60:63]
	v_mfma_f32_16x16x32_bf16 v[56:59], v[136:139], v[160:163], v[56:59]
	v_mfma_f32_16x16x32_bf16 v[48:51], v[128:131], v[168:171], v[48:51]
	v_mfma_f32_16x16x32_bf16 v[40:43], v[136:139], v[168:171], v[40:43]
	v_mfma_f32_16x16x32_bf16 v[32:35], v[128:131], v[176:179], v[32:35]
	v_mfma_f32_16x16x32_bf16 v[24:27], v[136:139], v[176:179], v[24:27]
	v_mfma_f32_16x16x32_bf16 v[16:19], v[128:131], v[184:187], v[16:19]
	v_mfma_f32_16x16x32_bf16 v[8:11], v[136:139], v[184:187], v[8:11]
	v_mfma_f32_16x16x32_bf16 v[60:63], v[132:135], v[164:167], v[60:63]
	v_mfma_f32_16x16x32_bf16 v[56:59], v[140:143], v[164:167], v[56:59]
	v_mfma_f32_16x16x32_bf16 v[48:51], v[132:135], v[172:175], v[48:51]
	v_mfma_f32_16x16x32_bf16 v[40:43], v[140:143], v[172:175], v[40:43]
	v_mfma_f32_16x16x32_bf16 v[32:35], v[132:135], v[180:183], v[32:35]
	v_mfma_f32_16x16x32_bf16 v[24:27], v[140:143], v[180:183], v[24:27]
	v_mfma_f32_16x16x32_bf16 v[16:19], v[132:135], v[188:191], v[16:19]
	v_mfma_f32_16x16x32_bf16 v[8:11], v[140:143], v[188:191], v[8:11]
	v_mfma_f32_16x16x32_bf16 v[52:55], v[144:147], v[160:163], v[52:55]
	v_mfma_f32_16x16x32_bf16 v[44:47], v[152:155], v[160:163], v[44:47]
	v_mfma_f32_16x16x32_bf16 v[36:39], v[144:147], v[168:171], v[36:39]
	v_mfma_f32_16x16x32_bf16 v[28:31], v[152:155], v[168:171], v[28:31]
	v_mfma_f32_16x16x32_bf16 v[20:23], v[144:147], v[176:179], v[20:23]
	v_mfma_f32_16x16x32_bf16 v[12:15], v[152:155], v[176:179], v[12:15]
	v_mfma_f32_16x16x32_bf16 v[4:7], v[144:147], v[184:187], v[4:7]
	v_mfma_f32_16x16x32_bf16 v[0:3], v[152:155], v[184:187], v[0:3]
	v_mfma_f32_16x16x32_bf16 v[52:55], v[148:151], v[164:167], v[52:55]
	v_mfma_f32_16x16x32_bf16 v[44:47], v[156:159], v[164:167], v[44:47]
	v_mfma_f32_16x16x32_bf16 v[36:39], v[148:151], v[172:175], v[36:39]
	v_mfma_f32_16x16x32_bf16 v[28:31], v[156:159], v[172:175], v[28:31]
	v_mfma_f32_16x16x32_bf16 v[20:23], v[148:151], v[180:183], v[20:23]
	v_mfma_f32_16x16x32_bf16 v[12:15], v[156:159], v[180:183], v[12:15]
	v_mfma_f32_16x16x32_bf16 v[4:7], v[148:151], v[188:191], v[4:7]
	v_mfma_f32_16x16x32_bf16 v[0:3], v[156:159], v[188:191], v[0:3]
	s_barrier
	s_setprio 0
	s_add_u32 s46, s46, 0x100
	s_addc_u32 s47, s47, 0
	s_add_u32 s69, s69, 0x100
	s_addc_u32 s70, s70, 0
	s_cmp_ge_i32 s71, s67
	s_mov_b32 s48, s71
	s_cbranch_scc0 .LBB0_938
	s_and_b64 vcc, exec, s[26:27]
	s_cbranch_vccnz .LBB0_943
	s_mov_b64 s[46:47], -1
	s_cmp_gt_i32 s18, -1
	v_lshl_or_b32 v218, s44, 8, v248
	s_cbranch_scc1 .LBB0_944

; #define PG8_STAGE(bufoff, gbase, voff) do { _Pragma("unroll") for (int _i = 0; _i < 2; ++_i) \
;         __builtin_amdgcn_global_load_lds((const unsigned*)((const char*)(gbase) + (voff)[_i]), (PG8_LAS unsigned*)(lds + (bufoff) + ldsw + _i * 8192), 16, 0, 0); } while (0)
; #define PG8_LDA(dst, b, h) do { _Pragma("unroll") for (int m = 0; m < 4; ++m) _Pragma("unroll") for (int k = 0; k < 2; ++k) dst[m][k] = *(const PG8_LAS bf16x8*)(lds + PG8_SA(b, h) + aoff + m * 2048 + k * 1024); } while (0)
; #define PG8_LDB(dst, b, h) do { _Pragma("unroll") for (int n = 0; n < 2; ++n) _Pragma("unroll") for (int k = 0; k < 2; ++k) dst[n][k] = *(const PG8_LAS bf16x8*)(lds + PG8_SB(b, h) + boff + n * 2048 + k * 1024); } while (0)
; #define PG8_WAIT_V(n) asm volatile("s_waitcnt vmcnt(" #n ")" ::: "memory")
; #define PG8_WAIT_L(n) asm volatile("s_waitcnt lgkmcnt(" #n ")" ::: "memory")
; #define PG8_BAR __builtin_amdgcn_s_barrier()
; template <class Epi, class Sched, bool ALIGN_EPI = false, bool SP2 = false>
; __device__ __forceinline__ void gemm_phase(PG8_LAS unsigned char* lds, const Gemm g, const Sched& S, const Epi& E) {
;     ...
;         const bool has_next = S.next(ui + 1, nxt);
;         const char* nA = has_next ? (const char*)g.A + (size_t)nxt.pm * tstep + (size_t)nxt.k0 * kstepA : cA; const char* nB = has_next ? (const char*)g.Bt + (size_t)nxt.pn * tstep + (size_t)nxt.k0 * kstepB : cB;
;         for (int t = 0; t < nt; t += 2) {
;             const bool last = (t == nt - 2);
;             const char* a1 = cA + (size_t)(t + 1) * kstepA;
;             const char* a2 = last ? nA : cA + (size_t)(t + 2) * kstepA; const char* b2 = last ? nB : cB + (size_t)(t + 2) * kstepB;
;             const char* a3 = a2 + kstepA; const char* b3 = b2 + kstepB;
;             if (last && has_next) S.a_ready(nxt);
;             if constexpr (SP2) {
;             PG8_LDB(B0, 0, 0); PG8_LDB(B1, 0, 1); PG8_SCHED; PG8_LDA(At, 0, 0); PG8_STAGE(PG8_SA(1, 1), a1 + hstepA, voffA);
;             PG8_WAIT_V(8); PG8_WAIT_L(0); PG8_BAR; PG8_MMA(0, 0, At, B0); PG8_MMA(0, 1, At, B1); PG8_BAR; PG8_SCHED;
;             PG8_LDA(At, 0, 1); PG8_STAGE(PG8_SB(0, 0), b2, voffB); PG8_STAGE(PG8_SB(0, 1), b2 + hstepB, voffB); PG8_STAGE(PG8_SA(0, 0), a2, voffA);
;             PG8_WAIT_V(8); PG8_WAIT_L(0); PG8_BAR; PG8_MMA(1, 0, At, B0); PG8_MMA(1, 1, At, B1); PG8_BAR; PG8_SCHED;
.LBB0_1113:
	s_sub_u32 s100, s42, 0x80000
	s_subb_u32 s101, s43, 0
	ds_read_b128 v[136:139], v181
	ds_read_b128 v[140:143], v181 offset:1024
	ds_read_b128 v[144:147], v181 offset:2048
	ds_read_b128 v[148:151], v181 offset:3072
	ds_read_b128 v[152:155], v182
	ds_read_b128 v[156:159], v182 offset:1024
	ds_read_b128 v[160:163], v182 offset:2048
	ds_read_b128 v[164:167], v182 offset:3072
	s_add_i32 s60, s44, 2
	s_add_u32 s45, s42, 0xfff80080
	s_addc_u32 s46, s43, -1
	s_cmp_eq_u32 s57, s44
	s_cselect_b32 s44, s39, s58
	s_cselect_b32 s47, s25, s46
	s_cselect_b32 s46, s29, s45
	s_cselect_b32 s45, s27, s59
	ds_read_b128 v[168:171], v183
	ds_read_b128 v[172:175], v183 offset:1024
	ds_read_b128 v[186:189], v183 offset:2048
	ds_read_b128 v[204:207], v183 offset:3072
	ds_read_b128 v[208:211], v183 offset:4096
	ds_read_b128 v[212:215], v183 offset:5120
	ds_read_b128 v[216:219], v183 offset:6144
	ds_read_b128 v[220:223], v183 offset:7168
	s_mov_b32 m0, s48
	s_nop 0
	global_load_lds_dwordx4 v128, s[100:101]
	s_mov_b32 m0, s49
	s_nop 0
	global_load_lds_dwordx4 v130, s[100:101]
	s_add_i32 m0, s13, 0xc000
	s_nop 0
	global_load_lds_dwordx4 v128, s[42:43]
	s_add_i32 m0, s13, 0xe000
	s_nop 0
	global_load_lds_dwordx4 v130, s[42:43]
	s_waitcnt vmcnt(8)
	s_waitcnt lgkmcnt(0)
	s_setprio 1
	s_barrier
	v_mfma_f32_16x16x32_bf16 v[124:127], v[136:139], v[168:171], v[124:127]
	v_mfma_f32_16x16x32_bf16 v[120:123], v[144:147], v[168:171], v[120:123]
	v_mfma_f32_16x16x32_bf16 v[108:111], v[136:139], v[186:189], v[108:111]
	v_mfma_f32_16x16x32_bf16 v[104:107], v[144:147], v[186:189], v[104:107]
	v_mfma_f32_16x16x32_bf16 v[92:95], v[136:139], v[208:211], v[92:95]
	v_mfma_f32_16x16x32_bf16 v[88:91], v[144:147], v[208:211], v[88:91]
	v_mfma_f32_16x16x32_bf16 v[76:79], v[136:139], v[216:219], v[76:79]
	v_mfma_f32_16x16x32_bf16 v[72:75], v[144:147], v[216:219], v[72:75]
	v_mfma_f32_16x16x32_bf16 v[124:127], v[140:143], v[172:175], v[124:127]
	v_mfma_f32_16x16x32_bf16 v[120:123], v[148:151], v[172:175], v[120:123]
	v_mfma_f32_16x16x32_bf16 v[108:111], v[140:143], v[204:207], v[108:111]
	v_mfma_f32_16x16x32_bf16 v[104:107], v[148:151], v[204:207], v[104:107]
	v_mfma_f32_16x16x32_bf16 v[92:95], v[140:143], v[212:215], v[92:95]
	v_mfma_f32_16x16x32_bf16 v[88:91], v[148:151], v[212:215], v[88:91]
	v_mfma_f32_16x16x32_bf16 v[76:79], v[140:143], v[220:223], v[76:79]
	v_mfma_f32_16x16x32_bf16 v[72:75], v[148:151], v[220:223], v[72:75]
	v_mfma_f32_16x16x32_bf16 v[116:119], v[152:155], v[168:171], v[116:119]
	v_mfma_f32_16x16x32_bf16 v[112:115], v[160:163], v[168:171], v[112:115]
	v_mfma_f32_16x16x32_bf16 v[100:103], v[152:155], v[186:189], v[100:103]
	v_mfma_f32_16x16x32_bf16 v[96:99], v[160:163], v[186:189], v[96:99]
	v_mfma_f32_16x16x32_bf16 v[84:87], v[152:155], v[208:211], v[84:87]
	v_mfma_f32_16x16x32_bf16 v[80:83], v[160:163], v[208:211], v[80:83]
	v_mfma_f32_16x16x32_bf16 v[68:71], v[152:155], v[216:219], v[68:71]
	v_mfma_f32_16x16x32_bf16 v[64:67], v[160:163], v[216:219], v[64:67]
	v_mfma_f32_16x16x32_bf16 v[116:119], v[156:159], v[172:175], v[116:119]
	v_mfma_f32_16x16x32_bf16 v[112:115], v[164:167], v[172:175], v[112:115]
	v_mfma_f32_16x16x32_bf16 v[100:103], v[156:159], v[204:207], v[100:103]
	v_mfma_f32_16x16x32_bf16 v[96:99], v[164:167], v[204:207], v[96:99]
	v_mfma_f32_16x16x32_bf16 v[84:87], v[156:159], v[212:215], v[84:87]
	v_mfma_f32_16x16x32_bf16 v[80:83], v[164:167], v[212:215], v[80:83]
	v_mfma_f32_16x16x32_bf16 v[68:71], v[156:159], v[220:223], v[68:71]
	v_mfma_f32_16x16x32_bf16 v[64:67], v[164:167], v[220:223], v[64:67]
	s_barrier
	s_add_u32 s98, s44, s20
	s_addc_u32 s99, s45, s21
	s_add_u32 s100, s46, s20
	s_addc_u32 s101, s47, s21
	s_setprio 0
	s_add_i32 s61, s51, s2
	s_mov_b32 m0, s61
	ds_read_b128 v[168:171], v183 offset:16384
	ds_read_b128 v[172:175], v183 offset:17408
	ds_read_b128 v[186:189], v183 offset:18432
	ds_read_b128 v[204:207], v183 offset:19456
	ds_read_b128 v[208:211], v183 offset:20480
	ds_read_b128 v[212:215], v183 offset:21504
	ds_read_b128 v[216:219], v183 offset:22528
	ds_read_b128 v[220:223], v183 offset:23552
	global_load_lds_dwordx4 v192, s[44:45]
	s_add_i32 m0, s61, 0x2000
	s_add_u32 s62, s44, 0x80000
	s_addc_u32 s63, s45, 0
	s_add_i32 s61, s52, s2
	global_load_lds_dwordx4 v196, s[44:45]
	s_mov_b32 m0, s61
	s_nop 0
	global_load_lds_dwordx4 v192, s[62:63]
	s_add_i32 m0, s61, 0x2000
	s_nop 0
	global_load_lds_dwordx4 v196, s[62:63]
	s_waitcnt vmcnt(6)
	s_waitcnt lgkmcnt(0)
	s_setprio 1
	s_barrier
	v_mfma_f32_16x16x32_bf16 v[60:63], v[136:139], v[168:171], v[60:63]
	v_mfma_f32_16x16x32_bf16 v[56:59], v[144:147], v[168:171], v[56:59]
	v_mfma_f32_16x16x32_bf16 v[44:47], v[136:139], v[186:189], v[44:47]
	v_mfma_f32_16x16x32_bf16 v[40:43], v[144:147], v[186:189], v[40:43]
	v_mfma_f32_16x16x32_bf16 v[28:31], v[136:139], v[208:211], v[28:31]
	v_mfma_f32_16x16x32_bf16 v[24:27], v[144:147], v[208:211], v[24:27]
	v_mfma_f32_16x16x32_bf16 v[12:15], v[136:139], v[216:219], v[12:15]
	v_mfma_f32_16x16x32_bf16 v[8:11], v[144:147], v[216:219], v[8:11]
	v_mfma_f32_16x16x32_bf16 v[60:63], v[140:143], v[172:175], v[60:63]
	v_mfma_f32_16x16x32_bf16 v[56:59], v[148:151], v[172:175], v[56:59]
	v_mfma_f32_16x16x32_bf16 v[44:47], v[140:143], v[204:207], v[44:47]
	v_mfma_f32_16x16x32_bf16 v[40:43], v[148:151], v[204:207], v[40:43]
	v_mfma_f32_16x16x32_bf16 v[28:31], v[140:143], v[212:215], v[28:31]
	v_mfma_f32_16x16x32_bf16 v[24:27], v[148:151], v[212:215], v[24:27]
	v_mfma_f32_16x16x32_bf16 v[12:15], v[140:143], v[220:223], v[12:15]
	v_mfma_f32_16x16x32_bf16 v[8:11], v[148:151], v[220:223], v[8:11]
	v_mfma_f32_16x16x32_bf16 v[52:55], v[152:155], v[168:171], v[52:55]
	v_mfma_f32_16x16x32_bf16 v[48:51], v[160:163], v[168:171], v[48:51]
	v_mfma_f32_16x16x32_bf16 v[36:39], v[152:155], v[186:189], v[36:39]
	v_mfma_f32_16x16x32_bf16 v[32:35], v[160:163], v[186:189], v[32:35]
	v_mfma_f32_16x16x32_bf16 v[20:23], v[152:155], v[208:211], v[20:23]
	v_mfma_f32_16x16x32_bf16 v[16:19], v[160:163], v[208:211], v[16:19]
	v_mfma_f32_16x16x32_bf16 v[4:7], v[152:155], v[216:219], v[4:7]
	v_mfma_f32_16x16x32_bf16 v[0:3], v[160:163], v[216:219], v[0:3]
	v_mfma_f32_16x16x32_bf16 v[52:55], v[156:159], v[172:175], v[52:55]
	v_mfma_f32_16x16x32_bf16 v[48:51], v[164:167], v[172:175], v[48:51]
	v_mfma_f32_16x16x32_bf16 v[36:39], v[156:159], v[204:207], v[36:39]
	v_mfma_f32_16x16x32_bf16 v[32:35], v[164:167], v[204:207], v[32:35]
	v_mfma_f32_16x16x32_bf16 v[20:23], v[156:159], v[212:215], v[20:23]
	v_mfma_f32_16x16x32_bf16 v[16:19], v[164:167], v[212:215], v[16:19]
	v_mfma_f32_16x16x32_bf16 v[4:7], v[156:159], v[220:223], v[4:7]
	v_mfma_f32_16x16x32_bf16 v[0:3], v[164:167], v[220:223], v[0:3]
	s_barrier
; #define PG8_STAGE(bufoff, gbase, voff) do { _Pragma("unroll") for (int _i = 0; _i < 2; ++_i) \
;         __builtin_amdgcn_global_load_lds((const unsigned*)((const char*)(gbase) + (voff)[_i]), (PG8_LAS unsigned*)(lds + (bufoff) + ldsw + _i * 8192), 16, 0, 0); } while (0)
; #define PG8_LDA(dst, b, h) do { _Pragma("unroll") for (int m = 0; m < 4; ++m) _Pragma("unroll") for (int k = 0; k < 2; ++k) dst[m][k] = *(const PG8_LAS bf16x8*)(lds + PG8_SA(b, h) + aoff + m * 2048 + k * 1024); } while (0)
; #define PG8_LDB(dst, b, h) do { _Pragma("unroll") for (int n = 0; n < 2; ++n) _Pragma("unroll") for (int k = 0; k < 2; ++k) dst[n][k] = *(const PG8_LAS bf16x8*)(lds + PG8_SB(b, h) + boff + n * 2048 + k * 1024); } while (0)
; #define PG8_MMA(ai, bj, At, Bt) do { __builtin_amdgcn_s_setprio(1); _Pragma("unroll") for (int m = 0; m < 4; ++m) _Pragma("unroll") for (int n = 0; n < 2; ++n) _Pragma("unroll") for (int k = 0; k < 2; ++k) \
;         acc[ai][bj][m][n] = __builtin_amdgcn_mfma_f32_16x16x32_bf16(Bt[n][k], At[m][k], acc[ai][bj][m][n], 0, 0, 0); __builtin_amdgcn_s_setprio(0); } while (0)
; #define PG8_WAIT_V(n) asm volatile("s_waitcnt vmcnt(" #n ")" ::: "memory")
; #define PG8_WAIT_L(n) asm volatile("s_waitcnt lgkmcnt(" #n ")" ::: "memory")
; #define PG8_BAR __builtin_amdgcn_s_barrier()
; #define PG8_SCHED __builtin_amdgcn_sched_barrier(0)
; template <class Epi, class Sched, bool ALIGN_EPI = false, bool SP2 = false>
; __device__ __forceinline__ void gemm_phase(PG8_LAS unsigned char* lds, const Gemm g, const Sched& S, const Epi& E) {
;     ...
;             PG8_LDB(B0, 1, 0); PG8_LDB(B1, 1, 1); PG8_SCHED; PG8_LDA(At, 1, 0); PG8_STAGE(PG8_SA(0, 1), a2 + hstepA, voffA);
;             PG8_WAIT_V(8); PG8_WAIT_L(0); PG8_BAR; PG8_MMA(0, 0, At, B0); PG8_MMA(0, 1, At, B1); PG8_BAR; PG8_SCHED;
;             PG8_LDA(At, 1, 1); PG8_STAGE(PG8_SB(1, 0), b3, voffB); PG8_STAGE(PG8_SB(1, 1), b3 + hstepB, voffB); PG8_STAGE(PG8_SA(1, 0), a3, voffA);
;             PG8_WAIT_V(8); PG8_WAIT_L(0); PG8_BAR; PG8_MMA(1, 0, At, B0); PG8_MMA(1, 1, At, B1); PG8_BAR; PG8_SCHED;
	s_setprio 0
	s_add_i32 s61, 0, 0x18000
	s_add_i32 s62, 0, 0x1c000
	v_add_u32_e32 v148, s61, v179
	v_add_u32_e32 v164, s62, v179
	ds_read_b128 v[136:139], v148
	ds_read_b128 v[140:143], v148 offset:1024
	ds_read_b128 v[144:147], v148 offset:2048
	ds_read_b128 v[148:151], v148 offset:3072
	ds_read_b128 v[152:155], v164
	ds_read_b128 v[156:159], v164 offset:1024
	ds_read_b128 v[160:163], v164 offset:2048
	ds_read_b128 v[164:167], v164 offset:3072
	s_mov_b32 m0, s13
	s_nop 0
	global_load_lds_dwordx4 v192, s[46:47]
	s_mov_b32 m0, s14
	s_nop 0
	global_load_lds_dwordx4 v196, s[46:47]
	s_add_u32 s46, s46, 0x80000
	s_addc_u32 s47, s47, 0
	s_mov_b32 m0, s15
	ds_read_b128 v[168:171], v183 offset:32768
	ds_read_b128 v[172:175], v183 offset:33792
	ds_read_b128 v[186:189], v183 offset:34816
	ds_read_b128 v[204:207], v183 offset:35840
	ds_read_b128 v[208:211], v183 offset:36864
	ds_read_b128 v[212:215], v183 offset:37888
	ds_read_b128 v[216:219], v183 offset:38912
	ds_read_b128 v[220:223], v183 offset:39936
	global_load_lds_dwordx4 v192, s[46:47]
	s_mov_b32 m0, s41
	s_nop 0
	global_load_lds_dwordx4 v196, s[46:47]
	s_waitcnt vmcnt(8)
	s_waitcnt lgkmcnt(0)
	s_setprio 1
	s_barrier
	v_mfma_f32_16x16x32_bf16 v[124:127], v[136:139], v[168:171], v[124:127]
	v_mfma_f32_16x16x32_bf16 v[120:123], v[144:147], v[168:171], v[120:123]
	v_mfma_f32_16x16x32_bf16 v[108:111], v[136:139], v[186:189], v[108:111]
	v_mfma_f32_16x16x32_bf16 v[104:107], v[144:147], v[186:189], v[104:107]
	v_mfma_f32_16x16x32_bf16 v[92:95], v[136:139], v[208:211], v[92:95]
	v_mfma_f32_16x16x32_bf16 v[88:91], v[144:147], v[208:211], v[88:91]
	v_mfma_f32_16x16x32_bf16 v[76:79], v[136:139], v[216:219], v[76:79]
	v_mfma_f32_16x16x32_bf16 v[72:75], v[144:147], v[216:219], v[72:75]
	v_mfma_f32_16x16x32_bf16 v[124:127], v[140:143], v[172:175], v[124:127]
	v_mfma_f32_16x16x32_bf16 v[120:123], v[148:151], v[172:175], v[120:123]
	v_mfma_f32_16x16x32_bf16 v[108:111], v[140:143], v[204:207], v[108:111]
	v_mfma_f32_16x16x32_bf16 v[104:107], v[148:151], v[204:207], v[104:107]
	v_mfma_f32_16x16x32_bf16 v[92:95], v[140:143], v[212:215], v[92:95]
	v_mfma_f32_16x16x32_bf16 v[88:91], v[148:151], v[212:215], v[88:91]
	v_mfma_f32_16x16x32_bf16 v[76:79], v[140:143], v[220:223], v[76:79]
	v_mfma_f32_16x16x32_bf16 v[72:75], v[148:151], v[220:223], v[72:75]
	v_mfma_f32_16x16x32_bf16 v[116:119], v[152:155], v[168:171], v[116:119]
	v_mfma_f32_16x16x32_bf16 v[112:115], v[160:163], v[168:171], v[112:115]
	v_mfma_f32_16x16x32_bf16 v[100:103], v[152:155], v[186:189], v[100:103]
	v_mfma_f32_16x16x32_bf16 v[96:99], v[160:163], v[186:189], v[96:99]
	v_mfma_f32_16x16x32_bf16 v[84:87], v[152:155], v[208:211], v[84:87]
	v_mfma_f32_16x16x32_bf16 v[80:83], v[160:163], v[208:211], v[80:83]
	v_mfma_f32_16x16x32_bf16 v[68:71], v[152:155], v[216:219], v[68:71]
	v_mfma_f32_16x16x32_bf16 v[64:67], v[160:163], v[216:219], v[64:67]
	v_mfma_f32_16x16x32_bf16 v[116:119], v[156:159], v[172:175], v[116:119]
	v_mfma_f32_16x16x32_bf16 v[112:115], v[164:167], v[172:175], v[112:115]
	v_mfma_f32_16x16x32_bf16 v[100:103], v[156:159], v[204:207], v[100:103]
	v_mfma_f32_16x16x32_bf16 v[96:99], v[164:167], v[204:207], v[96:99]
	v_mfma_f32_16x16x32_bf16 v[84:87], v[156:159], v[212:215], v[84:87]
	v_mfma_f32_16x16x32_bf16 v[80:83], v[164:167], v[212:215], v[80:83]
	v_mfma_f32_16x16x32_bf16 v[68:71], v[156:159], v[220:223], v[68:71]
	v_mfma_f32_16x16x32_bf16 v[64:67], v[164:167], v[220:223], v[64:67]
	s_barrier
	s_setprio 0
	s_add_i32 s46, s61, s2
	s_mov_b32 m0, s46
	ds_read_b128 v[168:171], v183 offset:49152
	ds_read_b128 v[172:175], v183 offset:50176
	ds_read_b128 v[186:189], v183 offset:51200
	ds_read_b128 v[204:207], v183 offset:52224
	ds_read_b128 v[208:211], v183 offset:53248
	ds_read_b128 v[212:215], v183 offset:54272
	ds_read_b128 v[216:219], v183 offset:55296
	ds_read_b128 v[220:223], v183 offset:56320
	global_load_lds_dwordx4 v192, s[98:99]
	s_add_i32 m0, s46, 0x2000
	s_add_u32 s44, s44, 0x80080
	s_addc_u32 s45, s45, 0
	s_add_i32 s46, s62, s2
	global_load_lds_dwordx4 v196, s[98:99]
	s_mov_b32 m0, s46
	s_nop 0
	global_load_lds_dwordx4 v192, s[44:45]
	s_add_i32 m0, s46, 0x2000
	s_nop 0
	global_load_lds_dwordx4 v196, s[44:45]
	s_waitcnt vmcnt(6)
	s_waitcnt lgkmcnt(0)
	s_setprio 1
	s_barrier
	v_mfma_f32_16x16x32_bf16 v[60:63], v[136:139], v[168:171], v[60:63]
	v_mfma_f32_16x16x32_bf16 v[56:59], v[144:147], v[168:171], v[56:59]
	v_mfma_f32_16x16x32_bf16 v[44:47], v[136:139], v[186:189], v[44:47]
	v_mfma_f32_16x16x32_bf16 v[40:43], v[144:147], v[186:189], v[40:43]
	v_mfma_f32_16x16x32_bf16 v[28:31], v[136:139], v[208:211], v[28:31]
	v_mfma_f32_16x16x32_bf16 v[24:27], v[144:147], v[208:211], v[24:27]
	v_mfma_f32_16x16x32_bf16 v[12:15], v[136:139], v[216:219], v[12:15]
	v_mfma_f32_16x16x32_bf16 v[8:11], v[144:147], v[216:219], v[8:11]
	v_mfma_f32_16x16x32_bf16 v[60:63], v[140:143], v[172:175], v[60:63]
	v_mfma_f32_16x16x32_bf16 v[56:59], v[148:151], v[172:175], v[56:59]
	v_mfma_f32_16x16x32_bf16 v[44:47], v[140:143], v[204:207], v[44:47]
	v_mfma_f32_16x16x32_bf16 v[40:43], v[148:151], v[204:207], v[40:43]
	v_mfma_f32_16x16x32_bf16 v[28:31], v[140:143], v[212:215], v[28:31]
	v_mfma_f32_16x16x32_bf16 v[24:27], v[148:151], v[212:215], v[24:27]
	v_mfma_f32_16x16x32_bf16 v[12:15], v[140:143], v[220:223], v[12:15]
	v_mfma_f32_16x16x32_bf16 v[8:11], v[148:151], v[220:223], v[8:11]
	v_mfma_f32_16x16x32_bf16 v[52:55], v[152:155], v[168:171], v[52:55]
	v_mfma_f32_16x16x32_bf16 v[48:51], v[160:163], v[168:171], v[48:51]
	v_mfma_f32_16x16x32_bf16 v[36:39], v[152:155], v[186:189], v[36:39]
	v_mfma_f32_16x16x32_bf16 v[32:35], v[160:163], v[186:189], v[32:35]
	v_mfma_f32_16x16x32_bf16 v[20:23], v[152:155], v[208:211], v[20:23]
	v_mfma_f32_16x16x32_bf16 v[16:19], v[160:163], v[208:211], v[16:19]
	v_mfma_f32_16x16x32_bf16 v[4:7], v[152:155], v[216:219], v[4:7]
	v_mfma_f32_16x16x32_bf16 v[0:3], v[160:163], v[216:219], v[0:3]
	v_mfma_f32_16x16x32_bf16 v[52:55], v[156:159], v[172:175], v[52:55]
	v_mfma_f32_16x16x32_bf16 v[48:51], v[164:167], v[172:175], v[48:51]
	v_mfma_f32_16x16x32_bf16 v[36:39], v[156:159], v[204:207], v[36:39]
	v_mfma_f32_16x16x32_bf16 v[32:35], v[164:167], v[204:207], v[32:35]
	v_mfma_f32_16x16x32_bf16 v[20:23], v[156:159], v[212:215], v[20:23]
	v_mfma_f32_16x16x32_bf16 v[16:19], v[164:167], v[212:215], v[16:19]
	v_mfma_f32_16x16x32_bf16 v[4:7], v[156:159], v[220:223], v[4:7]
	v_mfma_f32_16x16x32_bf16 v[0:3], v[164:167], v[220:223], v[0:3]
	s_barrier
	s_setprio 0
	s_add_u32 s42, s42, 0x100
	s_addc_u32 s43, s43, 0
	s_add_u32 s58, s58, 0x100
	s_addc_u32 s59, s59, 0
	s_cmp_ge_i32 s60, s56
	s_mov_b32 s44, s60
	s_cbranch_scc0 .LBB0_1113
	s_and_b64 vcc, exec, s[22:23]
	s_cbranch_vccnz .LBB0_1118
	s_mov_b64 s[42:43], -1
	s_cmp_gt_i32 s16, -1
	v_lshl_or_b32 v136, s40, 8, v180
	s_cbranch_scc1 .LBB0_1119

; #define PG8_STAGE(bufoff, gbase, voff) do { _Pragma("unroll") for (int _i = 0; _i < 2; ++_i) \
;         __builtin_amdgcn_global_load_lds((const unsigned*)((const char*)(gbase) + (voff)[_i]), (PG8_LAS unsigned*)(lds + (bufoff) + ldsw + _i * 8192), 16, 0, 0); } while (0)
; #define PG8_LDA(dst, b, h) do { _Pragma("unroll") for (int m = 0; m < 4; ++m) _Pragma("unroll") for (int k = 0; k < 2; ++k) dst[m][k] = *(const PG8_LAS bf16x8*)(lds + PG8_SA(b, h) + aoff + m * 2048 + k * 1024); } while (0)
; #define PG8_LDB(dst, b, h) do { _Pragma("unroll") for (int n = 0; n < 2; ++n) _Pragma("unroll") for (int k = 0; k < 2; ++k) dst[n][k] = *(const PG8_LAS bf16x8*)(lds + PG8_SB(b, h) + boff + n * 2048 + k * 1024); } while (0)
; #define PG8_WAIT_V(n) asm volatile("s_waitcnt vmcnt(" #n ")" ::: "memory")
; #define PG8_WAIT_L(n) asm volatile("s_waitcnt lgkmcnt(" #n ")" ::: "memory")
; #define PG8_BAR __builtin_amdgcn_s_barrier()
; template <class Epi, class Sched, bool ALIGN_EPI = false, bool SP2 = false>
; __device__ __forceinline__ void gemm_phase(PG8_LAS unsigned char* lds, const Gemm g, const Sched& S, const Epi& E) {
;     ...
;         const bool has_next = S.next(ui + 1, nxt);
;         const char* nA = has_next ? (const char*)g.A + (size_t)nxt.pm * tstep + (size_t)nxt.k0 * kstepA : cA; const char* nB = has_next ? (const char*)g.Bt + (size_t)nxt.pn * tstep + (size_t)nxt.k0 * kstepB : cB;
;         for (int t = 0; t < nt; t += 2) {
;             const bool last = (t == nt - 2);
;             const char* a1 = cA + (size_t)(t + 1) * kstepA;
;             const char* a2 = last ? nA : cA + (size_t)(t + 2) * kstepA; const char* b2 = last ? nB : cB + (size_t)(t + 2) * kstepB;
;             const char* a3 = a2 + kstepA; const char* b3 = b2 + kstepB;
;             if (last && has_next) S.a_ready(nxt);
;             if constexpr (SP2) {
;             PG8_LDB(B0, 0, 0); PG8_LDB(B1, 0, 1); PG8_SCHED; PG8_LDA(At, 0, 0); PG8_STAGE(PG8_SA(1, 1), a1 + hstepA, voffA);
;             PG8_WAIT_V(8); PG8_WAIT_L(0); PG8_BAR; PG8_MMA(0, 0, At, B0); PG8_MMA(0, 1, At, B1); PG8_BAR; PG8_SCHED;
;             PG8_LDA(At, 0, 1); PG8_STAGE(PG8_SB(0, 0), b2, voffB); PG8_STAGE(PG8_SB(0, 1), b2 + hstepB, voffB); PG8_STAGE(PG8_SA(0, 0), a2, voffA);
;             PG8_WAIT_V(8); PG8_WAIT_L(0); PG8_BAR; PG8_MMA(1, 0, At, B0); PG8_MMA(1, 1, At, B1); PG8_BAR; PG8_SCHED;
.LBB0_1339:
	s_sub_u32 s100, s34, 0x80000
	s_subb_u32 s101, s35, 0
	ds_read_b128 v[136:139], v129
	ds_read_b128 v[144:147], v129 offset:1024
	ds_read_b128 v[148:151], v129 offset:2048
	ds_read_b128 v[152:155], v129 offset:3072
	ds_read_b128 v[156:159], v141
	ds_read_b128 v[160:163], v141 offset:1024
	ds_read_b128 v[164:167], v141 offset:2048
	ds_read_b128 v[168:171], v141 offset:3072
	s_add_u32 s36, s34, 0xfff80080
	s_addc_u32 s37, s35, -1
	s_cmp_eq_u32 s53, 28
	s_cselect_b32 s39, s23, s37
	s_cselect_b32 s38, s49, s36
	s_cselect_b32 s37, s21, s52
	s_cselect_b32 s36, s50, s51
	ds_read_b128 v[172:175], v142
	ds_read_b128 v[176:179], v142 offset:1024
	ds_read_b128 v[180:183], v142 offset:2048
	ds_read_b128 v[184:187], v142 offset:3072
	ds_read_b128 v[188:191], v142 offset:4096
	ds_read_b128 v[204:207], v142 offset:5120
	ds_read_b128 v[208:211], v142 offset:6144
	ds_read_b128 v[212:215], v142 offset:7168
	s_mov_b32 m0, s43
	s_nop 0
	global_load_lds_dwordx4 v132, s[100:101]
	s_mov_b32 m0, s44
	s_nop 0
	global_load_lds_dwordx4 v134, s[100:101]
	s_add_i32 m0, s15, 0xc000
	s_nop 0
	global_load_lds_dwordx4 v132, s[34:35]
	s_add_i32 m0, s15, 0xe000
	s_nop 0
	global_load_lds_dwordx4 v134, s[34:35]
	s_waitcnt vmcnt(8)
	s_waitcnt lgkmcnt(0)
	s_setprio 1
	s_barrier
	v_mfma_f32_16x16x32_bf16 v[124:127], v[136:139], v[172:175], v[124:127]
	v_mfma_f32_16x16x32_bf16 v[120:123], v[148:151], v[172:175], v[120:123]
	v_mfma_f32_16x16x32_bf16 v[108:111], v[136:139], v[180:183], v[108:111]
	v_mfma_f32_16x16x32_bf16 v[104:107], v[148:151], v[180:183], v[104:107]
	v_mfma_f32_16x16x32_bf16 v[92:95], v[136:139], v[188:191], v[92:95]
	v_mfma_f32_16x16x32_bf16 v[88:91], v[148:151], v[188:191], v[88:91]
	v_mfma_f32_16x16x32_bf16 v[76:79], v[136:139], v[208:211], v[76:79]
	v_mfma_f32_16x16x32_bf16 v[72:75], v[148:151], v[208:211], v[72:75]
	v_mfma_f32_16x16x32_bf16 v[124:127], v[144:147], v[176:179], v[124:127]
	v_mfma_f32_16x16x32_bf16 v[120:123], v[152:155], v[176:179], v[120:123]
	v_mfma_f32_16x16x32_bf16 v[108:111], v[144:147], v[184:187], v[108:111]
	v_mfma_f32_16x16x32_bf16 v[104:107], v[152:155], v[184:187], v[104:107]
	v_mfma_f32_16x16x32_bf16 v[92:95], v[144:147], v[204:207], v[92:95]
	v_mfma_f32_16x16x32_bf16 v[88:91], v[152:155], v[204:207], v[88:91]
	v_mfma_f32_16x16x32_bf16 v[76:79], v[144:147], v[212:215], v[76:79]
	v_mfma_f32_16x16x32_bf16 v[72:75], v[152:155], v[212:215], v[72:75]
	v_mfma_f32_16x16x32_bf16 v[116:119], v[156:159], v[172:175], v[116:119]
	v_mfma_f32_16x16x32_bf16 v[112:115], v[164:167], v[172:175], v[112:115]
	v_mfma_f32_16x16x32_bf16 v[100:103], v[156:159], v[180:183], v[100:103]
	v_mfma_f32_16x16x32_bf16 v[96:99], v[164:167], v[180:183], v[96:99]
	v_mfma_f32_16x16x32_bf16 v[84:87], v[156:159], v[188:191], v[84:87]
	v_mfma_f32_16x16x32_bf16 v[80:83], v[164:167], v[188:191], v[80:83]
	v_mfma_f32_16x16x32_bf16 v[68:71], v[156:159], v[208:211], v[68:71]
	v_mfma_f32_16x16x32_bf16 v[64:67], v[164:167], v[208:211], v[64:67]
	v_mfma_f32_16x16x32_bf16 v[116:119], v[160:163], v[176:179], v[116:119]
	v_mfma_f32_16x16x32_bf16 v[112:115], v[168:171], v[176:179], v[112:115]
	v_mfma_f32_16x16x32_bf16 v[100:103], v[160:163], v[184:187], v[100:103]
	v_mfma_f32_16x16x32_bf16 v[96:99], v[168:171], v[184:187], v[96:99]
	v_mfma_f32_16x16x32_bf16 v[84:87], v[160:163], v[204:207], v[84:87]
	v_mfma_f32_16x16x32_bf16 v[80:83], v[168:171], v[204:207], v[80:83]
	v_mfma_f32_16x16x32_bf16 v[68:71], v[160:163], v[212:215], v[68:71]
	v_mfma_f32_16x16x32_bf16 v[64:67], v[168:171], v[212:215], v[64:67]
	s_barrier
	s_add_u32 s98, s38, s12
	s_addc_u32 s99, s39, s13
	s_setprio 0
	s_add_i32 s54, s46, s2
	s_mov_b32 m0, s54
	ds_read_b128 v[172:175], v142 offset:16384
	ds_read_b128 v[176:179], v142 offset:17408
	ds_read_b128 v[180:183], v142 offset:18432
	ds_read_b128 v[184:187], v142 offset:19456
	ds_read_b128 v[188:191], v142 offset:20480
	ds_read_b128 v[204:207], v142 offset:21504
	ds_read_b128 v[208:211], v142 offset:22528
	ds_read_b128 v[212:215], v142 offset:23552
	global_load_lds_dwordx4 v194, s[36:37]
	s_add_i32 m0, s54, 0x2000
	s_add_u32 s54, s36, 0x4000
	s_addc_u32 s55, s37, 0
	s_add_i32 s56, s47, s2
	global_load_lds_dwordx4 v198, s[36:37]
	s_mov_b32 m0, s56
	s_nop 0
	global_load_lds_dwordx4 v194, s[54:55]
	s_add_i32 m0, s56, 0x2000
	s_nop 0
	global_load_lds_dwordx4 v198, s[54:55]
	s_waitcnt vmcnt(6)
	s_waitcnt lgkmcnt(0)
	s_setprio 1
	s_barrier
	v_mfma_f32_16x16x32_bf16 v[60:63], v[136:139], v[172:175], v[60:63]
	v_mfma_f32_16x16x32_bf16 v[56:59], v[148:151], v[172:175], v[56:59]
	v_mfma_f32_16x16x32_bf16 v[44:47], v[136:139], v[180:183], v[44:47]
	v_mfma_f32_16x16x32_bf16 v[40:43], v[148:151], v[180:183], v[40:43]
	v_mfma_f32_16x16x32_bf16 v[28:31], v[136:139], v[188:191], v[28:31]
	v_mfma_f32_16x16x32_bf16 v[24:27], v[148:151], v[188:191], v[24:27]
	v_mfma_f32_16x16x32_bf16 v[12:15], v[136:139], v[208:211], v[12:15]
	v_mfma_f32_16x16x32_bf16 v[8:11], v[148:151], v[208:211], v[8:11]
	v_mfma_f32_16x16x32_bf16 v[60:63], v[144:147], v[176:179], v[60:63]
	v_mfma_f32_16x16x32_bf16 v[56:59], v[152:155], v[176:179], v[56:59]
	v_mfma_f32_16x16x32_bf16 v[44:47], v[144:147], v[184:187], v[44:47]
	v_mfma_f32_16x16x32_bf16 v[40:43], v[152:155], v[184:187], v[40:43]
	v_mfma_f32_16x16x32_bf16 v[28:31], v[144:147], v[204:207], v[28:31]
	v_mfma_f32_16x16x32_bf16 v[24:27], v[152:155], v[204:207], v[24:27]
	v_mfma_f32_16x16x32_bf16 v[12:15], v[144:147], v[212:215], v[12:15]
	v_mfma_f32_16x16x32_bf16 v[8:11], v[152:155], v[212:215], v[8:11]
	v_mfma_f32_16x16x32_bf16 v[52:55], v[156:159], v[172:175], v[52:55]
	v_mfma_f32_16x16x32_bf16 v[48:51], v[164:167], v[172:175], v[48:51]
	v_mfma_f32_16x16x32_bf16 v[36:39], v[156:159], v[180:183], v[36:39]
	v_mfma_f32_16x16x32_bf16 v[32:35], v[164:167], v[180:183], v[32:35]
	v_mfma_f32_16x16x32_bf16 v[20:23], v[156:159], v[188:191], v[20:23]
	v_mfma_f32_16x16x32_bf16 v[16:19], v[164:167], v[188:191], v[16:19]
	v_mfma_f32_16x16x32_bf16 v[4:7], v[156:159], v[208:211], v[4:7]
	v_mfma_f32_16x16x32_bf16 v[0:3], v[164:167], v[208:211], v[0:3]
	v_mfma_f32_16x16x32_bf16 v[52:55], v[160:163], v[176:179], v[52:55]
	v_mfma_f32_16x16x32_bf16 v[48:51], v[168:171], v[176:179], v[48:51]
	v_mfma_f32_16x16x32_bf16 v[36:39], v[160:163], v[184:187], v[36:39]
	v_mfma_f32_16x16x32_bf16 v[32:35], v[168:171], v[184:187], v[32:35]
	v_mfma_f32_16x16x32_bf16 v[20:23], v[160:163], v[204:207], v[20:23]
	v_mfma_f32_16x16x32_bf16 v[16:19], v[168:171], v[204:207], v[16:19]
	v_mfma_f32_16x16x32_bf16 v[4:7], v[160:163], v[212:215], v[4:7]
	v_mfma_f32_16x16x32_bf16 v[0:3], v[168:171], v[212:215], v[0:3]
	s_barrier
; #define PG8_STAGE(bufoff, gbase, voff) do { _Pragma("unroll") for (int _i = 0; _i < 2; ++_i) \
;         __builtin_amdgcn_global_load_lds((const unsigned*)((const char*)(gbase) + (voff)[_i]), (PG8_LAS unsigned*)(lds + (bufoff) + ldsw + _i * 8192), 16, 0, 0); } while (0)
; #define PG8_LDA(dst, b, h) do { _Pragma("unroll") for (int m = 0; m < 4; ++m) _Pragma("unroll") for (int k = 0; k < 2; ++k) dst[m][k] = *(const PG8_LAS bf16x8*)(lds + PG8_SA(b, h) + aoff + m * 2048 + k * 1024); } while (0)
; #define PG8_LDB(dst, b, h) do { _Pragma("unroll") for (int n = 0; n < 2; ++n) _Pragma("unroll") for (int k = 0; k < 2; ++k) dst[n][k] = *(const PG8_LAS bf16x8*)(lds + PG8_SB(b, h) + boff + n * 2048 + k * 1024); } while (0)
; #define PG8_MMA(ai, bj, At, Bt) do { __builtin_amdgcn_s_setprio(1); _Pragma("unroll") for (int m = 0; m < 4; ++m) _Pragma("unroll") for (int n = 0; n < 2; ++n) _Pragma("unroll") for (int k = 0; k < 2; ++k) \
;         acc[ai][bj][m][n] = __builtin_amdgcn_mfma_f32_16x16x32_bf16(Bt[n][k], At[m][k], acc[ai][bj][m][n], 0, 0, 0); __builtin_amdgcn_s_setprio(0); } while (0)
; #define PG8_WAIT_V(n) asm volatile("s_waitcnt vmcnt(" #n ")" ::: "memory")
; #define PG8_WAIT_L(n) asm volatile("s_waitcnt lgkmcnt(" #n ")" ::: "memory")
; #define PG8_BAR __builtin_amdgcn_s_barrier()
; #define PG8_SCHED __builtin_amdgcn_sched_barrier(0)
; template <class Epi, class Sched, bool ALIGN_EPI = false, bool SP2 = false>
; __device__ __forceinline__ void gemm_phase(PG8_LAS unsigned char* lds, const Gemm g, const Sched& S, const Epi& E) {
;     ...
;             PG8_LDB(B0, 1, 0); PG8_LDB(B1, 1, 1); PG8_SCHED; PG8_LDA(At, 1, 0); PG8_STAGE(PG8_SA(0, 1), a2 + hstepA, voffA);
;             PG8_WAIT_V(8); PG8_WAIT_L(0); PG8_BAR; PG8_MMA(0, 0, At, B0); PG8_MMA(0, 1, At, B1); PG8_BAR; PG8_SCHED;
;             PG8_LDA(At, 1, 1); PG8_STAGE(PG8_SB(1, 0), b3, voffB); PG8_STAGE(PG8_SB(1, 1), b3 + hstepB, voffB); PG8_STAGE(PG8_SA(1, 0), a3, voffA);
;             PG8_WAIT_V(8); PG8_WAIT_L(0); PG8_BAR; PG8_MMA(1, 0, At, B0); PG8_MMA(1, 1, At, B1); PG8_BAR; PG8_SCHED;
	s_setprio 0
	s_add_i32 s54, 0, 0x18000
	s_add_i32 s55, 0, 0x1c000
	v_add_u32_e32 v152, s54, v140
	v_add_u32_e32 v168, s55, v140
	ds_read_b128 v[136:139], v152
	ds_read_b128 v[144:147], v152 offset:1024
	ds_read_b128 v[148:151], v152 offset:2048
	ds_read_b128 v[152:155], v152 offset:3072
	ds_read_b128 v[156:159], v168
	ds_read_b128 v[160:163], v168 offset:1024
	ds_read_b128 v[164:167], v168 offset:2048
	ds_read_b128 v[168:171], v168 offset:3072
	s_mov_b32 m0, s15
	s_nop 0
	global_load_lds_dwordx4 v192, s[38:39]
	s_mov_b32 m0, s40
	s_nop 0
	global_load_lds_dwordx4 v196, s[38:39]
	s_add_u32 s38, s38, 0x80000
	s_addc_u32 s39, s39, 0
	s_mov_b32 m0, s41
	ds_read_b128 v[172:175], v142 offset:32768
	ds_read_b128 v[176:179], v142 offset:33792
	ds_read_b128 v[180:183], v142 offset:34816
	ds_read_b128 v[184:187], v142 offset:35840
	ds_read_b128 v[188:191], v142 offset:36864
	ds_read_b128 v[204:207], v142 offset:37888
	ds_read_b128 v[208:211], v142 offset:38912
	ds_read_b128 v[212:215], v142 offset:39936
	global_load_lds_dwordx4 v192, s[38:39]
	s_mov_b32 m0, s42
	s_nop 0
	global_load_lds_dwordx4 v196, s[38:39]
	s_waitcnt vmcnt(8)
	s_waitcnt lgkmcnt(0)
	s_setprio 1
	s_barrier
	v_mfma_f32_16x16x32_bf16 v[124:127], v[136:139], v[172:175], v[124:127]
	v_mfma_f32_16x16x32_bf16 v[120:123], v[148:151], v[172:175], v[120:123]
	v_mfma_f32_16x16x32_bf16 v[108:111], v[136:139], v[180:183], v[108:111]
	v_mfma_f32_16x16x32_bf16 v[104:107], v[148:151], v[180:183], v[104:107]
	v_mfma_f32_16x16x32_bf16 v[92:95], v[136:139], v[188:191], v[92:95]
	v_mfma_f32_16x16x32_bf16 v[88:91], v[148:151], v[188:191], v[88:91]
	v_mfma_f32_16x16x32_bf16 v[76:79], v[136:139], v[208:211], v[76:79]
	v_mfma_f32_16x16x32_bf16 v[72:75], v[148:151], v[208:211], v[72:75]
	v_mfma_f32_16x16x32_bf16 v[124:127], v[144:147], v[176:179], v[124:127]
	v_mfma_f32_16x16x32_bf16 v[120:123], v[152:155], v[176:179], v[120:123]
	v_mfma_f32_16x16x32_bf16 v[108:111], v[144:147], v[184:187], v[108:111]
	v_mfma_f32_16x16x32_bf16 v[104:107], v[152:155], v[184:187], v[104:107]
	v_mfma_f32_16x16x32_bf16 v[92:95], v[144:147], v[204:207], v[92:95]
	v_mfma_f32_16x16x32_bf16 v[88:91], v[152:155], v[204:207], v[88:91]
	v_mfma_f32_16x16x32_bf16 v[76:79], v[144:147], v[212:215], v[76:79]
	v_mfma_f32_16x16x32_bf16 v[72:75], v[152:155], v[212:215], v[72:75]
	v_mfma_f32_16x16x32_bf16 v[116:119], v[156:159], v[172:175], v[116:119]
	v_mfma_f32_16x16x32_bf16 v[112:115], v[164:167], v[172:175], v[112:115]
	v_mfma_f32_16x16x32_bf16 v[100:103], v[156:159], v[180:183], v[100:103]
	v_mfma_f32_16x16x32_bf16 v[96:99], v[164:167], v[180:183], v[96:99]
	v_mfma_f32_16x16x32_bf16 v[84:87], v[156:159], v[188:191], v[84:87]
	v_mfma_f32_16x16x32_bf16 v[80:83], v[164:167], v[188:191], v[80:83]
	v_mfma_f32_16x16x32_bf16 v[68:71], v[156:159], v[208:211], v[68:71]
	v_mfma_f32_16x16x32_bf16 v[64:67], v[164:167], v[208:211], v[64:67]
	v_mfma_f32_16x16x32_bf16 v[116:119], v[160:163], v[176:179], v[116:119]
	v_mfma_f32_16x16x32_bf16 v[112:115], v[168:171], v[176:179], v[112:115]
	v_mfma_f32_16x16x32_bf16 v[100:103], v[160:163], v[184:187], v[100:103]
	v_mfma_f32_16x16x32_bf16 v[96:99], v[168:171], v[184:187], v[96:99]
	v_mfma_f32_16x16x32_bf16 v[84:87], v[160:163], v[204:207], v[84:87]
	v_mfma_f32_16x16x32_bf16 v[80:83], v[168:171], v[204:207], v[80:83]
	v_mfma_f32_16x16x32_bf16 v[68:71], v[160:163], v[212:215], v[68:71]
	v_mfma_f32_16x16x32_bf16 v[64:67], v[168:171], v[212:215], v[64:67]
	s_barrier
	s_setprio 0
	s_add_u32 s38, s36, 0x8000
	s_addc_u32 s39, s37, 0
	s_add_i32 s54, s54, s2
	s_mov_b32 m0, s54
	ds_read_b128 v[172:175], v142 offset:49152
	ds_read_b128 v[176:179], v142 offset:50176
	ds_read_b128 v[180:183], v142 offset:51200
	ds_read_b128 v[184:187], v142 offset:52224
	ds_read_b128 v[188:191], v142 offset:53248
	ds_read_b128 v[204:207], v142 offset:54272
	ds_read_b128 v[208:211], v142 offset:55296
	ds_read_b128 v[212:215], v142 offset:56320
	global_load_lds_dwordx4 v194, s[38:39]
	s_add_i32 m0, s54, 0x2000
	s_add_u32 s36, s36, 0xc000
	s_addc_u32 s37, s37, 0
	global_load_lds_dwordx4 v198, s[38:39]
	s_add_i32 s38, s55, s2
	s_mov_b32 m0, s38
	s_nop 0
	global_load_lds_dwordx4 v194, s[36:37]
	s_add_i32 m0, s38, 0x2000
	s_nop 0
	global_load_lds_dwordx4 v198, s[36:37]
	s_waitcnt vmcnt(6)
	s_waitcnt lgkmcnt(0)
	s_setprio 1
	s_barrier
	v_mfma_f32_16x16x32_bf16 v[60:63], v[136:139], v[172:175], v[60:63]
	v_mfma_f32_16x16x32_bf16 v[56:59], v[148:151], v[172:175], v[56:59]
	v_mfma_f32_16x16x32_bf16 v[44:47], v[136:139], v[180:183], v[44:47]
	v_mfma_f32_16x16x32_bf16 v[40:43], v[148:151], v[180:183], v[40:43]
	v_mfma_f32_16x16x32_bf16 v[28:31], v[136:139], v[188:191], v[28:31]
	v_mfma_f32_16x16x32_bf16 v[24:27], v[148:151], v[188:191], v[24:27]
	v_mfma_f32_16x16x32_bf16 v[12:15], v[136:139], v[208:211], v[12:15]
	v_mfma_f32_16x16x32_bf16 v[8:11], v[148:151], v[208:211], v[8:11]
	v_mfma_f32_16x16x32_bf16 v[60:63], v[144:147], v[176:179], v[60:63]
	v_mfma_f32_16x16x32_bf16 v[56:59], v[152:155], v[176:179], v[56:59]
	v_mfma_f32_16x16x32_bf16 v[44:47], v[144:147], v[184:187], v[44:47]
	v_mfma_f32_16x16x32_bf16 v[40:43], v[152:155], v[184:187], v[40:43]
	v_mfma_f32_16x16x32_bf16 v[28:31], v[144:147], v[204:207], v[28:31]
	v_mfma_f32_16x16x32_bf16 v[24:27], v[152:155], v[204:207], v[24:27]
	v_mfma_f32_16x16x32_bf16 v[12:15], v[144:147], v[212:215], v[12:15]
	v_mfma_f32_16x16x32_bf16 v[8:11], v[152:155], v[212:215], v[8:11]
	v_mfma_f32_16x16x32_bf16 v[52:55], v[156:159], v[172:175], v[52:55]
	v_mfma_f32_16x16x32_bf16 v[48:51], v[164:167], v[172:175], v[48:51]
	v_mfma_f32_16x16x32_bf16 v[36:39], v[156:159], v[180:183], v[36:39]
	v_mfma_f32_16x16x32_bf16 v[32:35], v[164:167], v[180:183], v[32:35]
	v_mfma_f32_16x16x32_bf16 v[20:23], v[156:159], v[188:191], v[20:23]
	v_mfma_f32_16x16x32_bf16 v[16:19], v[164:167], v[188:191], v[16:19]
	v_mfma_f32_16x16x32_bf16 v[4:7], v[156:159], v[208:211], v[4:7]
	v_mfma_f32_16x16x32_bf16 v[0:3], v[164:167], v[208:211], v[0:3]
	v_mfma_f32_16x16x32_bf16 v[52:55], v[160:163], v[176:179], v[52:55]
	v_mfma_f32_16x16x32_bf16 v[48:51], v[168:171], v[176:179], v[48:51]
	v_mfma_f32_16x16x32_bf16 v[36:39], v[160:163], v[184:187], v[36:39]
	v_mfma_f32_16x16x32_bf16 v[32:35], v[168:171], v[184:187], v[32:35]
	v_mfma_f32_16x16x32_bf16 v[20:23], v[160:163], v[204:207], v[20:23]
	v_mfma_f32_16x16x32_bf16 v[16:19], v[168:171], v[204:207], v[16:19]
	v_mfma_f32_16x16x32_bf16 v[4:7], v[160:163], v[212:215], v[4:7]
	v_mfma_f32_16x16x32_bf16 v[0:3], v[168:171], v[212:215], v[0:3]
	s_barrier
	s_setprio 0
	s_add_i32 s53, s53, 2
	s_add_u32 s51, s51, 0x10000
	s_addc_u32 s52, s52, 0
	s_add_u32 s34, s34, 0x100
	s_addc_u32 s35, s35, 0
	s_cmp_gt_u32 s53, 29
	s_cbranch_scc0 .LBB0_1339
	s_and_b64 vcc, exec, s[18:19]
	s_cbranch_vccz .LBB0_1342
	s_barrier

; #define PG8_STAGE(bufoff, gbase, voff) do { _Pragma("unroll") for (int _i = 0; _i < 2; ++_i) \
;         __builtin_amdgcn_global_load_lds((const unsigned*)((const char*)(gbase) + (voff)[_i]), (PG8_LAS unsigned*)(lds + (bufoff) + ldsw + _i * 8192), 16, 0, 0); } while (0)
; #define PG8_LDA(dst, b, h) do { _Pragma("unroll") for (int m = 0; m < 4; ++m) _Pragma("unroll") for (int k = 0; k < 2; ++k) dst[m][k] = *(const PG8_LAS bf16x8*)(lds + PG8_SA(b, h) + aoff + m * 2048 + k * 1024); } while (0)
; #define PG8_LDB(dst, b, h) do { _Pragma("unroll") for (int n = 0; n < 2; ++n) _Pragma("unroll") for (int k = 0; k < 2; ++k) dst[n][k] = *(const PG8_LAS bf16x8*)(lds + PG8_SB(b, h) + boff + n * 2048 + k * 1024); } while (0)
; #define PG8_WAIT_V(n) asm volatile("s_waitcnt vmcnt(" #n ")" ::: "memory")
; #define PG8_WAIT_L(n) asm volatile("s_waitcnt lgkmcnt(" #n ")" ::: "memory")
; #define PG8_BAR __builtin_amdgcn_s_barrier()
; template <class Epi, class Sched, bool ALIGN_EPI = false, bool SP2 = false>
; __device__ __forceinline__ void gemm_phase(PG8_LAS unsigned char* lds, const Gemm g, const Sched& S, const Epi& E) {
;     ...
;         const bool has_next = S.next(ui + 1, nxt);
;         const char* nA = has_next ? (const char*)g.A + (size_t)nxt.pm * tstep + (size_t)nxt.k0 * kstepA : cA; const char* nB = has_next ? (const char*)g.Bt + (size_t)nxt.pn * tstep + (size_t)nxt.k0 * kstepB : cB;
;         for (int t = 0; t < nt; t += 2) {
;             const bool last = (t == nt - 2);
;             const char* a1 = cA + (size_t)(t + 1) * kstepA;
;             const char* a2 = last ? nA : cA + (size_t)(t + 2) * kstepA; const char* b2 = last ? nB : cB + (size_t)(t + 2) * kstepB;
;             const char* a3 = a2 + kstepA; const char* b3 = b2 + kstepB;
;             if (last && has_next) S.a_ready(nxt);
;             if constexpr (SP2) {
;             PG8_LDB(B0, 0, 0); PG8_LDB(B1, 0, 1); PG8_SCHED; PG8_LDA(At, 0, 0); PG8_STAGE(PG8_SA(1, 1), a1 + hstepA, voffA);
;             PG8_WAIT_V(8); PG8_WAIT_L(0); PG8_BAR; PG8_MMA(0, 0, At, B0); PG8_MMA(0, 1, At, B1); PG8_BAR; PG8_SCHED;
;             PG8_LDA(At, 0, 1); PG8_STAGE(PG8_SB(0, 0), b2, voffB); PG8_STAGE(PG8_SB(0, 1), b2 + hstepB, voffB); PG8_STAGE(PG8_SA(0, 0), a2, voffA);
;             PG8_WAIT_V(8); PG8_WAIT_L(0); PG8_BAR; PG8_MMA(1, 0, At, B0); PG8_MMA(1, 1, At, B1); PG8_BAR; PG8_SCHED;
.LBB0_1421:
	s_sub_u32 s100, s40, 0x4000
	s_subb_u32 s101, s41, 0
	ds_read_b128 v[142:145], v191
	ds_read_b128 v[146:149], v191 offset:1024
	ds_read_b128 v[150:153], v191 offset:2048
	ds_read_b128 v[154:157], v191 offset:3072
	ds_read_b128 v[158:161], v192
	ds_read_b128 v[162:165], v192 offset:1024
	ds_read_b128 v[166:169], v192 offset:2048
	ds_read_b128 v[170:173], v192 offset:3072
	s_add_i32 s79, s42, 2
	s_add_u32 s43, s40, 0x4000
	s_addc_u32 s44, s41, 0
	s_cmp_eq_u32 s35, s42
	s_cselect_b32 s46, s36, s43
	s_cselect_b32 s47, s37, s44
	s_cselect_b32 s44, s38, s77
	s_cselect_b32 s45, s39, s78
	s_add_u32 s42, s46, 0x8000
	s_addc_u32 s43, s47, 0
	ds_read_b128 v[174:177], v193
	ds_read_b128 v[178:181], v193 offset:1024
	ds_read_b128 v[182:185], v193 offset:2048
	ds_read_b128 v[194:197], v193 offset:3072
	ds_read_b128 v[198:201], v193 offset:4096
	ds_read_b128 v[202:205], v193 offset:5120
	ds_read_b128 v[206:209], v193 offset:6144
	ds_read_b128 v[210:213], v193 offset:7168
	s_mov_b32 m0, s50
	s_nop 0
	global_load_lds_dwordx4 v134, s[100:101]
	s_mov_b32 m0, s51
	s_nop 0
	global_load_lds_dwordx4 v136, s[100:101]
	s_add_i32 m0, s10, 0xc000
	s_nop 0
	global_load_lds_dwordx4 v134, s[40:41]
	s_add_i32 m0, s10, 0xe000
	s_nop 0
	global_load_lds_dwordx4 v136, s[40:41]
	s_waitcnt vmcnt(8)
	s_waitcnt lgkmcnt(0)
	s_setprio 1
	s_barrier
	v_mfma_f32_16x16x32_bf16 v[124:127], v[142:145], v[174:177], v[124:127]
	v_mfma_f32_16x16x32_bf16 v[120:123], v[150:153], v[174:177], v[120:123]
	v_mfma_f32_16x16x32_bf16 v[108:111], v[142:145], v[182:185], v[108:111]
	v_mfma_f32_16x16x32_bf16 v[104:107], v[150:153], v[182:185], v[104:107]
	v_mfma_f32_16x16x32_bf16 v[92:95], v[142:145], v[198:201], v[92:95]
	v_mfma_f32_16x16x32_bf16 v[88:91], v[150:153], v[198:201], v[88:91]
	v_mfma_f32_16x16x32_bf16 v[76:79], v[142:145], v[206:209], v[76:79]
	v_mfma_f32_16x16x32_bf16 v[72:75], v[150:153], v[206:209], v[72:75]
	v_mfma_f32_16x16x32_bf16 v[124:127], v[146:149], v[178:181], v[124:127]
	v_mfma_f32_16x16x32_bf16 v[120:123], v[154:157], v[178:181], v[120:123]
	v_mfma_f32_16x16x32_bf16 v[108:111], v[146:149], v[194:197], v[108:111]
	v_mfma_f32_16x16x32_bf16 v[104:107], v[154:157], v[194:197], v[104:107]
	v_mfma_f32_16x16x32_bf16 v[92:95], v[146:149], v[202:205], v[92:95]
	v_mfma_f32_16x16x32_bf16 v[88:91], v[154:157], v[202:205], v[88:91]
	v_mfma_f32_16x16x32_bf16 v[76:79], v[146:149], v[210:213], v[76:79]
	v_mfma_f32_16x16x32_bf16 v[72:75], v[154:157], v[210:213], v[72:75]
	v_mfma_f32_16x16x32_bf16 v[116:119], v[158:161], v[174:177], v[116:119]
	v_mfma_f32_16x16x32_bf16 v[112:115], v[166:169], v[174:177], v[112:115]
	v_mfma_f32_16x16x32_bf16 v[100:103], v[158:161], v[182:185], v[100:103]
	v_mfma_f32_16x16x32_bf16 v[96:99], v[166:169], v[182:185], v[96:99]
	v_mfma_f32_16x16x32_bf16 v[84:87], v[158:161], v[198:201], v[84:87]
	v_mfma_f32_16x16x32_bf16 v[80:83], v[166:169], v[198:201], v[80:83]
	v_mfma_f32_16x16x32_bf16 v[68:71], v[158:161], v[206:209], v[68:71]
	v_mfma_f32_16x16x32_bf16 v[64:67], v[166:169], v[206:209], v[64:67]
	v_mfma_f32_16x16x32_bf16 v[116:119], v[162:165], v[178:181], v[116:119]
	v_mfma_f32_16x16x32_bf16 v[112:115], v[170:173], v[178:181], v[112:115]
	v_mfma_f32_16x16x32_bf16 v[100:103], v[162:165], v[194:197], v[100:103]
	v_mfma_f32_16x16x32_bf16 v[96:99], v[170:173], v[194:197], v[96:99]
	v_mfma_f32_16x16x32_bf16 v[84:87], v[162:165], v[202:205], v[84:87]
	v_mfma_f32_16x16x32_bf16 v[80:83], v[170:173], v[202:205], v[80:83]
	v_mfma_f32_16x16x32_bf16 v[68:71], v[162:165], v[210:213], v[68:71]
	v_mfma_f32_16x16x32_bf16 v[64:67], v[170:173], v[210:213], v[64:67]
	s_barrier
	s_setprio 0
	s_add_i32 s80, s52, s2
	s_mov_b32 m0, s80
	ds_read_b128 v[174:177], v193 offset:16384
	ds_read_b128 v[178:181], v193 offset:17408
	ds_read_b128 v[182:185], v193 offset:18432
	ds_read_b128 v[194:197], v193 offset:19456
	ds_read_b128 v[198:201], v193 offset:20480
	ds_read_b128 v[202:205], v193 offset:21504
	ds_read_b128 v[206:209], v193 offset:22528
	ds_read_b128 v[210:213], v193 offset:23552
	global_load_lds_dwordx4 v128, s[44:45]
	s_add_i32 m0, s80, 0x2000
	s_add_u32 s80, s44, 0x4000
	s_addc_u32 s81, s45, 0
	s_add_i32 s82, s53, s2
	global_load_lds_dwordx4 v130, s[44:45]
	s_mov_b32 m0, s82
	s_nop 0
	global_load_lds_dwordx4 v128, s[80:81]
	s_add_i32 m0, s82, 0x2000
	s_nop 0
	global_load_lds_dwordx4 v130, s[80:81]
	s_waitcnt vmcnt(6)
	s_waitcnt lgkmcnt(0)
	s_setprio 1
	s_barrier
	v_mfma_f32_16x16x32_bf16 v[60:63], v[142:145], v[174:177], v[60:63]
	v_mfma_f32_16x16x32_bf16 v[56:59], v[150:153], v[174:177], v[56:59]
	v_mfma_f32_16x16x32_bf16 v[44:47], v[142:145], v[182:185], v[44:47]
	v_mfma_f32_16x16x32_bf16 v[40:43], v[150:153], v[182:185], v[40:43]
	v_mfma_f32_16x16x32_bf16 v[28:31], v[142:145], v[198:201], v[28:31]
	v_mfma_f32_16x16x32_bf16 v[24:27], v[150:153], v[198:201], v[24:27]
	v_mfma_f32_16x16x32_bf16 v[12:15], v[142:145], v[206:209], v[12:15]
	v_mfma_f32_16x16x32_bf16 v[8:11], v[150:153], v[206:209], v[8:11]
	v_mfma_f32_16x16x32_bf16 v[60:63], v[146:149], v[178:181], v[60:63]
	v_mfma_f32_16x16x32_bf16 v[56:59], v[154:157], v[178:181], v[56:59]
	v_mfma_f32_16x16x32_bf16 v[44:47], v[146:149], v[194:197], v[44:47]
	v_mfma_f32_16x16x32_bf16 v[40:43], v[154:157], v[194:197], v[40:43]
	v_mfma_f32_16x16x32_bf16 v[28:31], v[146:149], v[202:205], v[28:31]
	v_mfma_f32_16x16x32_bf16 v[24:27], v[154:157], v[202:205], v[24:27]
	v_mfma_f32_16x16x32_bf16 v[12:15], v[146:149], v[210:213], v[12:15]
	v_mfma_f32_16x16x32_bf16 v[8:11], v[154:157], v[210:213], v[8:11]
	v_mfma_f32_16x16x32_bf16 v[52:55], v[158:161], v[174:177], v[52:55]
	v_mfma_f32_16x16x32_bf16 v[48:51], v[166:169], v[174:177], v[48:51]
	v_mfma_f32_16x16x32_bf16 v[36:39], v[158:161], v[182:185], v[36:39]
	v_mfma_f32_16x16x32_bf16 v[32:35], v[166:169], v[182:185], v[32:35]
	v_mfma_f32_16x16x32_bf16 v[20:23], v[158:161], v[198:201], v[20:23]
	v_mfma_f32_16x16x32_bf16 v[16:19], v[166:169], v[198:201], v[16:19]
	v_mfma_f32_16x16x32_bf16 v[4:7], v[158:161], v[206:209], v[4:7]
	v_mfma_f32_16x16x32_bf16 v[0:3], v[166:169], v[206:209], v[0:3]
	v_mfma_f32_16x16x32_bf16 v[52:55], v[162:165], v[178:181], v[52:55]
	v_mfma_f32_16x16x32_bf16 v[48:51], v[170:173], v[178:181], v[48:51]
	v_mfma_f32_16x16x32_bf16 v[36:39], v[162:165], v[194:197], v[36:39]
	v_mfma_f32_16x16x32_bf16 v[32:35], v[170:173], v[194:197], v[32:35]
	v_mfma_f32_16x16x32_bf16 v[20:23], v[162:165], v[202:205], v[20:23]
	v_mfma_f32_16x16x32_bf16 v[16:19], v[170:173], v[202:205], v[16:19]
	v_mfma_f32_16x16x32_bf16 v[4:7], v[162:165], v[210:213], v[4:7]
	v_mfma_f32_16x16x32_bf16 v[0:3], v[170:173], v[210:213], v[0:3]
	s_barrier
; #define PG8_STAGE(bufoff, gbase, voff) do { _Pragma("unroll") for (int _i = 0; _i < 2; ++_i) \
;         __builtin_amdgcn_global_load_lds((const unsigned*)((const char*)(gbase) + (voff)[_i]), (PG8_LAS unsigned*)(lds + (bufoff) + ldsw + _i * 8192), 16, 0, 0); } while (0)
; #define PG8_LDA(dst, b, h) do { _Pragma("unroll") for (int m = 0; m < 4; ++m) _Pragma("unroll") for (int k = 0; k < 2; ++k) dst[m][k] = *(const PG8_LAS bf16x8*)(lds + PG8_SA(b, h) + aoff + m * 2048 + k * 1024); } while (0)
; #define PG8_LDB(dst, b, h) do { _Pragma("unroll") for (int n = 0; n < 2; ++n) _Pragma("unroll") for (int k = 0; k < 2; ++k) dst[n][k] = *(const PG8_LAS bf16x8*)(lds + PG8_SB(b, h) + boff + n * 2048 + k * 1024); } while (0)
; #define PG8_MMA(ai, bj, At, Bt) do { __builtin_amdgcn_s_setprio(1); _Pragma("unroll") for (int m = 0; m < 4; ++m) _Pragma("unroll") for (int n = 0; n < 2; ++n) _Pragma("unroll") for (int k = 0; k < 2; ++k) \
;         acc[ai][bj][m][n] = __builtin_amdgcn_mfma_f32_16x16x32_bf16(Bt[n][k], At[m][k], acc[ai][bj][m][n], 0, 0, 0); __builtin_amdgcn_s_setprio(0); } while (0)
; #define PG8_WAIT_V(n) asm volatile("s_waitcnt vmcnt(" #n ")" ::: "memory")
; #define PG8_WAIT_L(n) asm volatile("s_waitcnt lgkmcnt(" #n ")" ::: "memory")
; #define PG8_BAR __builtin_amdgcn_s_barrier()
; #define PG8_SCHED __builtin_amdgcn_sched_barrier(0)
; template <class Epi, class Sched, bool ALIGN_EPI = false, bool SP2 = false>
; __device__ __forceinline__ void gemm_phase(PG8_LAS unsigned char* lds, const Gemm g, const Sched& S, const Epi& E) {
;     ...
;             PG8_LDB(B0, 1, 0); PG8_LDB(B1, 1, 1); PG8_SCHED; PG8_LDA(At, 1, 0); PG8_STAGE(PG8_SA(0, 1), a2 + hstepA, voffA);
;             PG8_WAIT_V(8); PG8_WAIT_L(0); PG8_BAR; PG8_MMA(0, 0, At, B0); PG8_MMA(0, 1, At, B1); PG8_BAR; PG8_SCHED;
;             PG8_LDA(At, 1, 1); PG8_STAGE(PG8_SB(1, 0), b3, voffB); PG8_STAGE(PG8_SB(1, 1), b3 + hstepB, voffB); PG8_STAGE(PG8_SA(1, 0), a3, voffA);
;             PG8_WAIT_V(8); PG8_WAIT_L(0); PG8_BAR; PG8_MMA(1, 0, At, B0); PG8_MMA(1, 1, At, B1); PG8_BAR; PG8_SCHED;
	s_setprio 0
	s_add_i32 s80, 0, 0x18000
	v_add_u32_e32 v132, s80, v189
	s_add_i32 s81, 0, 0x1c000
	ds_read_b128 v[142:145], v132
	ds_read_b128 v[146:149], v132 offset:1024
	ds_read_b128 v[150:153], v132 offset:2048
	ds_read_b128 v[154:157], v132 offset:3072
	v_add_u32_e32 v132, s81, v189
	ds_read_b128 v[158:161], v132
	ds_read_b128 v[162:165], v132 offset:1024
	ds_read_b128 v[166:169], v132 offset:2048
	ds_read_b128 v[170:173], v132 offset:3072
	s_mov_b32 m0, s10
	s_nop 0
	global_load_lds_dwordx4 v128, s[46:47]
	s_mov_b32 m0, s14
	s_nop 0
	global_load_lds_dwordx4 v130, s[46:47]
	s_add_u32 s46, s46, 0x4000
	s_addc_u32 s47, s47, 0
	s_mov_b32 m0, s15
	ds_read_b128 v[174:177], v193 offset:32768
	ds_read_b128 v[178:181], v193 offset:33792
	ds_read_b128 v[182:185], v193 offset:34816
	ds_read_b128 v[194:197], v193 offset:35840
	ds_read_b128 v[198:201], v193 offset:36864
	ds_read_b128 v[202:205], v193 offset:37888
	ds_read_b128 v[206:209], v193 offset:38912
	ds_read_b128 v[210:213], v193 offset:39936
	global_load_lds_dwordx4 v128, s[46:47]
	s_mov_b32 m0, s48
	s_nop 0
	global_load_lds_dwordx4 v130, s[46:47]
	s_waitcnt vmcnt(8)
	s_waitcnt lgkmcnt(0)
	s_setprio 1
	s_barrier
	v_mfma_f32_16x16x32_bf16 v[124:127], v[142:145], v[174:177], v[124:127]
	v_mfma_f32_16x16x32_bf16 v[120:123], v[150:153], v[174:177], v[120:123]
	v_mfma_f32_16x16x32_bf16 v[108:111], v[142:145], v[182:185], v[108:111]
	v_mfma_f32_16x16x32_bf16 v[104:107], v[150:153], v[182:185], v[104:107]
	v_mfma_f32_16x16x32_bf16 v[92:95], v[142:145], v[198:201], v[92:95]
	v_mfma_f32_16x16x32_bf16 v[88:91], v[150:153], v[198:201], v[88:91]
	v_mfma_f32_16x16x32_bf16 v[76:79], v[142:145], v[206:209], v[76:79]
	v_mfma_f32_16x16x32_bf16 v[72:75], v[150:153], v[206:209], v[72:75]
	v_mfma_f32_16x16x32_bf16 v[124:127], v[146:149], v[178:181], v[124:127]
	v_mfma_f32_16x16x32_bf16 v[120:123], v[154:157], v[178:181], v[120:123]
	v_mfma_f32_16x16x32_bf16 v[108:111], v[146:149], v[194:197], v[108:111]
	v_mfma_f32_16x16x32_bf16 v[104:107], v[154:157], v[194:197], v[104:107]
	v_mfma_f32_16x16x32_bf16 v[92:95], v[146:149], v[202:205], v[92:95]
	v_mfma_f32_16x16x32_bf16 v[88:91], v[154:157], v[202:205], v[88:91]
	v_mfma_f32_16x16x32_bf16 v[76:79], v[146:149], v[210:213], v[76:79]
	v_mfma_f32_16x16x32_bf16 v[72:75], v[154:157], v[210:213], v[72:75]
	v_mfma_f32_16x16x32_bf16 v[116:119], v[158:161], v[174:177], v[116:119]
	v_mfma_f32_16x16x32_bf16 v[112:115], v[166:169], v[174:177], v[112:115]
	v_mfma_f32_16x16x32_bf16 v[100:103], v[158:161], v[182:185], v[100:103]
	v_mfma_f32_16x16x32_bf16 v[96:99], v[166:169], v[182:185], v[96:99]
	v_mfma_f32_16x16x32_bf16 v[84:87], v[158:161], v[198:201], v[84:87]
	v_mfma_f32_16x16x32_bf16 v[80:83], v[166:169], v[198:201], v[80:83]
	v_mfma_f32_16x16x32_bf16 v[68:71], v[158:161], v[206:209], v[68:71]
	v_mfma_f32_16x16x32_bf16 v[64:67], v[166:169], v[206:209], v[64:67]
	v_mfma_f32_16x16x32_bf16 v[116:119], v[162:165], v[178:181], v[116:119]
	v_mfma_f32_16x16x32_bf16 v[112:115], v[170:173], v[178:181], v[112:115]
	v_mfma_f32_16x16x32_bf16 v[100:103], v[162:165], v[194:197], v[100:103]
	v_mfma_f32_16x16x32_bf16 v[96:99], v[170:173], v[194:197], v[96:99]
	v_mfma_f32_16x16x32_bf16 v[84:87], v[162:165], v[202:205], v[84:87]
	v_mfma_f32_16x16x32_bf16 v[80:83], v[170:173], v[202:205], v[80:83]
	v_mfma_f32_16x16x32_bf16 v[68:71], v[162:165], v[210:213], v[68:71]
	v_mfma_f32_16x16x32_bf16 v[64:67], v[170:173], v[210:213], v[64:67]
	s_barrier
	s_setprio 0
	s_add_u32 s46, s44, 0x8000
	s_addc_u32 s47, s45, 0
	s_add_i32 s80, s80, s2
	s_mov_b32 m0, s80
	ds_read_b128 v[174:177], v193 offset:49152
	ds_read_b128 v[178:181], v193 offset:50176
	ds_read_b128 v[182:185], v193 offset:51200
	ds_read_b128 v[194:197], v193 offset:52224
	ds_read_b128 v[198:201], v193 offset:53248
	ds_read_b128 v[202:205], v193 offset:54272
	ds_read_b128 v[206:209], v193 offset:55296
	ds_read_b128 v[210:213], v193 offset:56320
	global_load_lds_dwordx4 v128, s[46:47]
	s_add_i32 m0, s80, 0x2000
	s_add_u32 s44, s44, 0xc000
	s_addc_u32 s45, s45, 0
	global_load_lds_dwordx4 v130, s[46:47]
	s_add_i32 s46, s81, s2
	s_mov_b32 m0, s46
	s_nop 0
	global_load_lds_dwordx4 v128, s[44:45]
	s_add_i32 m0, s46, 0x2000
	s_nop 0
	global_load_lds_dwordx4 v130, s[44:45]
	s_waitcnt vmcnt(6)
	s_waitcnt lgkmcnt(0)
	s_setprio 1
	s_barrier
	v_mfma_f32_16x16x32_bf16 v[60:63], v[142:145], v[174:177], v[60:63]
	v_mfma_f32_16x16x32_bf16 v[56:59], v[150:153], v[174:177], v[56:59]
	v_mfma_f32_16x16x32_bf16 v[44:47], v[142:145], v[182:185], v[44:47]
	v_mfma_f32_16x16x32_bf16 v[40:43], v[150:153], v[182:185], v[40:43]
	v_mfma_f32_16x16x32_bf16 v[28:31], v[142:145], v[198:201], v[28:31]
	v_mfma_f32_16x16x32_bf16 v[24:27], v[150:153], v[198:201], v[24:27]
	v_mfma_f32_16x16x32_bf16 v[12:15], v[142:145], v[206:209], v[12:15]
	v_mfma_f32_16x16x32_bf16 v[8:11], v[150:153], v[206:209], v[8:11]
	v_mfma_f32_16x16x32_bf16 v[60:63], v[146:149], v[178:181], v[60:63]
	v_mfma_f32_16x16x32_bf16 v[56:59], v[154:157], v[178:181], v[56:59]
	v_mfma_f32_16x16x32_bf16 v[44:47], v[146:149], v[194:197], v[44:47]
	v_mfma_f32_16x16x32_bf16 v[40:43], v[154:157], v[194:197], v[40:43]
	v_mfma_f32_16x16x32_bf16 v[28:31], v[146:149], v[202:205], v[28:31]
	v_mfma_f32_16x16x32_bf16 v[24:27], v[154:157], v[202:205], v[24:27]
	v_mfma_f32_16x16x32_bf16 v[12:15], v[146:149], v[210:213], v[12:15]
	v_mfma_f32_16x16x32_bf16 v[8:11], v[154:157], v[210:213], v[8:11]
	v_mfma_f32_16x16x32_bf16 v[52:55], v[158:161], v[174:177], v[52:55]
	v_mfma_f32_16x16x32_bf16 v[48:51], v[166:169], v[174:177], v[48:51]
	v_mfma_f32_16x16x32_bf16 v[36:39], v[158:161], v[182:185], v[36:39]
	v_mfma_f32_16x16x32_bf16 v[32:35], v[166:169], v[182:185], v[32:35]
	v_mfma_f32_16x16x32_bf16 v[20:23], v[158:161], v[198:201], v[20:23]
	v_mfma_f32_16x16x32_bf16 v[16:19], v[166:169], v[198:201], v[16:19]
	v_mfma_f32_16x16x32_bf16 v[4:7], v[158:161], v[206:209], v[4:7]
	v_mfma_f32_16x16x32_bf16 v[0:3], v[166:169], v[206:209], v[0:3]
	v_mfma_f32_16x16x32_bf16 v[52:55], v[162:165], v[178:181], v[52:55]
	v_mfma_f32_16x16x32_bf16 v[48:51], v[170:173], v[178:181], v[48:51]
	v_mfma_f32_16x16x32_bf16 v[36:39], v[162:165], v[194:197], v[36:39]
	v_mfma_f32_16x16x32_bf16 v[32:35], v[170:173], v[194:197], v[32:35]
	v_mfma_f32_16x16x32_bf16 v[20:23], v[162:165], v[202:205], v[20:23]
	v_mfma_f32_16x16x32_bf16 v[16:19], v[170:173], v[202:205], v[16:19]
	v_mfma_f32_16x16x32_bf16 v[4:7], v[162:165], v[210:213], v[4:7]
	v_mfma_f32_16x16x32_bf16 v[0:3], v[170:173], v[210:213], v[0:3]
	s_barrier
	s_setprio 0
	s_add_u32 s40, s40, 0x10000
	s_addc_u32 s41, s41, 0
	s_add_u32 s77, s77, 0x10000
	s_addc_u32 s78, s78, 0
	s_cmp_ge_i32 s79, s76
	s_mov_b32 s42, s79
	s_cbranch_scc0 .LBB0_1421
	s_and_b64 vcc, exec, s[20:21]
	s_cbranch_vccnz .LBB0_1426
	s_mov_b64 s[40:41], -1
	s_cmp_gt_i32 s16, -1
	v_lshl_or_b32 v142, s75, 8, v190
	s_cbranch_scc1 .LBB0_1427
